# hoist P5 epilogue row-scale loads, pre-touch P4 residual lines, task redistribution, sharded first barrier
# speedup vs baseline: 1.0378x; 1.0049x over previous
; #define PG8_STAGE(bufoff, gbase, voff) do { _Pragma("unroll") for (int _i = 0; _i < 2; ++_i) \
;         __builtin_amdgcn_global_load_lds((const unsigned*)((const char*)(gbase) + (voff)[_i]), (LAS unsigned*)(lds + (bufoff) + ldsw + _i * 8192), 16, 0, 0); } while (0)
; #define PG8_LDA(dst, b, h) do { _Pragma("unroll") for (int m = 0; m < 4; ++m) _Pragma("unroll") for (int k = 0; k < 2; ++k) dst[m][k] = *(const LAS h16x8*)(lds + PG8_SA(b, h) + aoff + m * 2048 + k * 1024); } while (0)
; #define PG8_LDB(dst, b, h) do { _Pragma("unroll") for (int n = 0; n < 2; ++n) _Pragma("unroll") for (int k = 0; k < 2; ++k) dst[n][k] = *(const LAS h16x8*)(lds + PG8_SB(b, h) + boff + n * 2048 + k * 1024); } while (0)
; #define PG8_MMA(ai, bj, At, Bt) do { __builtin_amdgcn_s_setprio(1); _Pragma("unroll") for (int m = 0; m < 4; ++m) _Pragma("unroll") for (int n = 0; n < 2; ++n) _Pragma("unroll") for (int k = 0; k < 2; ++k) \
;         acc[ai][bj][m][n] = __builtin_amdgcn_mfma_f32_16x16x32_f16(Bt[n][k], At[m][k], acc[ai][bj][m][n], 0, 0, 0); __builtin_amdgcn_s_setprio(0); } while (0)
; #define PG8_WAIT_V(n) asm volatile("s_waitcnt vmcnt(" #n ")" ::: "memory")
; #define PG8_WAIT_L(n) asm volatile("s_waitcnt lgkmcnt(" #n ")" ::: "memory")
; #define PG8_BAR __builtin_amdgcn_s_barrier()
; #define PG8_SCHED __builtin_amdgcn_sched_barrier(0)
; template <class Epi>
; __device__ __forceinline__ void gemm_phase(LAS unsigned char* lds, const Gemm g, const StaticOrder& S, const Epi& E) {
;     ...
;             PG8_LDB(B0, 0, 0); PG8_SCHED; PG8_LDA(At, 0, 0); PG8_STAGE(PG8_SA(1, 1), a1 + hstep, voffA);
;             PG8_WAIT_L(8); PG8_BAR; PG8_WAIT_L(0); PG8_MMA(0, 0, At, B0); PG8_BAR; PG8_SCHED;
;             PG8_LDB(B1, 0, 1); PG8_STAGE(PG8_SB(0, 0), b2, voffB);
;             PG8_BAR; PG8_WAIT_L(0); PG8_MMA(0, 1, At, B1); PG8_BAR;
;             PG8_LDA(At, 0, 1); PG8_STAGE(PG8_SA(0, 0), a2, voffA);
;             PG8_BAR; PG8_WAIT_L(0); PG8_MMA(1, 0, At, B0); PG8_BAR; PG8_SCHED;
;             PG8_STAGE(PG8_SB(0, 1), b2 + hstep, voffB);
;             PG8_WAIT_V(6); PG8_BAR; PG8_MMA(1, 1, At, B1); PG8_BAR;
.LBB0_422:
	ds_read_b128 v[162:165], v145
	ds_read_b128 v[168:171], v145 offset:1024
	ds_read_b128 v[172:175], v145 offset:2048
	ds_read_b128 v[176:179], v145 offset:3072
	s_add_u32 s28, s26, 0xfffc0080
	s_addc_u32 s29, s27, -1
	s_cmp_eq_u32 s50, 12
	s_cselect_b32 s31, s17, s29
	s_cselect_b32 s30, s23, s28
	s_cselect_b32 s29, s13, s49
	s_cselect_b32 s28, s47, s48
	v_lshl_add_u64 v[212:213], s[26:27], 0, v[154:155]
	s_add_i32 m0, s25, 0xc000
	ds_read_b128 v[180:183], v147
	ds_read_b128 v[184:187], v147 offset:1024
	ds_read_b128 v[188:191], v147 offset:2048
	ds_read_b128 v[192:195], v147 offset:3072
	ds_read_b128 v[196:199], v147 offset:4096
	ds_read_b128 v[200:203], v147 offset:5120
	ds_read_b128 v[204:207], v147 offset:6144
	ds_read_b128 v[208:211], v147 offset:7168
	global_load_lds_dwordx4 v[212:213], off
	v_lshl_add_u64 v[212:213], s[26:27], 0, v[156:157]
	s_add_i32 m0, s25, 0xe000
	s_nop 0
	global_load_lds_dwordx4 v[212:213], off
	s_waitcnt lgkmcnt(8)
	s_barrier
	s_waitcnt lgkmcnt(0)
	s_setprio 1
	s_waitcnt lgkmcnt(0)
	v_mfma_f32_16x16x32_f16 v[124:127], v[162:165], v[180:183], v[124:127]
	v_mfma_f32_16x16x32_f16 v[120:123], v[172:175], v[180:183], v[120:123]
	v_mfma_f32_16x16x32_f16 v[108:111], v[162:165], v[188:191], v[108:111]
	v_mfma_f32_16x16x32_f16 v[104:107], v[172:175], v[188:191], v[104:107]
	v_mfma_f32_16x16x32_f16 v[92:95], v[162:165], v[196:199], v[92:95]
	v_mfma_f32_16x16x32_f16 v[88:91], v[172:175], v[196:199], v[88:91]
	v_mfma_f32_16x16x32_f16 v[76:79], v[162:165], v[204:207], v[76:79]
	v_mfma_f32_16x16x32_f16 v[72:75], v[172:175], v[204:207], v[72:75]
	v_mfma_f32_16x16x32_f16 v[124:127], v[168:171], v[184:187], v[124:127]
	v_mfma_f32_16x16x32_f16 v[120:123], v[176:179], v[184:187], v[120:123]
	v_mfma_f32_16x16x32_f16 v[108:111], v[168:171], v[192:195], v[108:111]
	v_mfma_f32_16x16x32_f16 v[104:107], v[176:179], v[192:195], v[104:107]
	v_mfma_f32_16x16x32_f16 v[92:95], v[168:171], v[200:203], v[92:95]
	v_mfma_f32_16x16x32_f16 v[88:91], v[176:179], v[200:203], v[88:91]
	v_mfma_f32_16x16x32_f16 v[76:79], v[168:171], v[208:211], v[76:79]
	v_mfma_f32_16x16x32_f16 v[72:75], v[176:179], v[208:211], v[72:75]
	s_setprio 0
	s_barrier
	s_add_i32 s51, s45, s37
	v_lshl_add_u64 v[228:229], s[28:29], 0, v[148:149]
	s_mov_b32 m0, s51
	ds_read_b128 v[212:215], v166
	ds_read_b128 v[216:219], v166 offset:1024
	ds_read_b128 v[220:223], v166 offset:2048
	ds_read_b128 v[224:227], v166 offset:3072
	global_load_lds_dwordx4 v[228:229], off
	v_lshl_add_u64 v[230:231], s[28:29], 0, v[152:153]
	s_add_i32 m0, s51, 0x2000
	s_nop 0
	global_load_lds_dwordx4 v[230:231], off
	s_barrier
	s_waitcnt lgkmcnt(0)
	s_setprio 1
	s_waitcnt lgkmcnt(0)
	v_mfma_f32_16x16x32_f16 v[116:119], v[212:215], v[180:183], v[116:119]
	v_mfma_f32_16x16x32_f16 v[112:115], v[220:223], v[180:183], v[112:115]
	v_mfma_f32_16x16x32_f16 v[100:103], v[212:215], v[188:191], v[100:103]
	v_mfma_f32_16x16x32_f16 v[96:99], v[220:223], v[188:191], v[96:99]
	v_mfma_f32_16x16x32_f16 v[84:87], v[212:215], v[196:199], v[84:87]
	v_mfma_f32_16x16x32_f16 v[80:83], v[220:223], v[196:199], v[80:83]
	v_mfma_f32_16x16x32_f16 v[68:71], v[212:215], v[204:207], v[68:71]
	v_mfma_f32_16x16x32_f16 v[64:67], v[220:223], v[204:207], v[64:67]
	v_mfma_f32_16x16x32_f16 v[116:119], v[216:219], v[184:187], v[116:119]
	v_mfma_f32_16x16x32_f16 v[112:115], v[224:227], v[184:187], v[112:115]
	v_mfma_f32_16x16x32_f16 v[100:103], v[216:219], v[192:195], v[100:103]
	v_mfma_f32_16x16x32_f16 v[96:99], v[224:227], v[192:195], v[96:99]
	v_mfma_f32_16x16x32_f16 v[84:87], v[216:219], v[200:203], v[84:87]
	v_mfma_f32_16x16x32_f16 v[80:83], v[224:227], v[200:203], v[80:83]
	v_mfma_f32_16x16x32_f16 v[68:71], v[216:219], v[208:211], v[68:71]
	v_mfma_f32_16x16x32_f16 v[64:67], v[224:227], v[208:211], v[64:67]
	s_setprio 0
	s_mov_b32 m0, s25
	v_lshl_add_u64 v[232:233], s[30:31], 0, v[142:143]
	s_barrier
	ds_read_b128 v[180:183], v147 offset:16384
	ds_read_b128 v[184:187], v147 offset:17408
	ds_read_b128 v[188:191], v147 offset:18432
	ds_read_b128 v[192:195], v147 offset:19456
	ds_read_b128 v[196:199], v147 offset:20480
	ds_read_b128 v[200:203], v147 offset:21504
	ds_read_b128 v[204:207], v147 offset:22528
	ds_read_b128 v[208:211], v147 offset:23552
	global_load_lds_dwordx4 v[232:233], off
	v_lshl_add_u64 v[234:235], s[30:31], 0, v[150:151]
	s_mov_b32 m0, s38
	s_nop 0
	global_load_lds_dwordx4 v[234:235], off
	s_barrier
	s_waitcnt lgkmcnt(0)
	s_setprio 1
	s_waitcnt lgkmcnt(0)
	v_mfma_f32_16x16x32_f16 v[60:63], v[162:165], v[180:183], v[60:63]
	v_mfma_f32_16x16x32_f16 v[56:59], v[172:175], v[180:183], v[56:59]
	v_mfma_f32_16x16x32_f16 v[44:47], v[162:165], v[188:191], v[44:47]
	v_mfma_f32_16x16x32_f16 v[40:43], v[172:175], v[188:191], v[40:43]
	v_mfma_f32_16x16x32_f16 v[28:31], v[162:165], v[196:199], v[28:31]
	v_mfma_f32_16x16x32_f16 v[24:27], v[172:175], v[196:199], v[24:27]
	v_mfma_f32_16x16x32_f16 v[12:15], v[162:165], v[204:207], v[12:15]
	v_mfma_f32_16x16x32_f16 v[8:11], v[172:175], v[204:207], v[8:11]
	v_mfma_f32_16x16x32_f16 v[60:63], v[168:171], v[184:187], v[60:63]
	v_mfma_f32_16x16x32_f16 v[56:59], v[176:179], v[184:187], v[56:59]
	v_mfma_f32_16x16x32_f16 v[44:47], v[168:171], v[192:195], v[44:47]
	v_mfma_f32_16x16x32_f16 v[40:43], v[176:179], v[192:195], v[40:43]
	v_mfma_f32_16x16x32_f16 v[28:31], v[168:171], v[200:203], v[28:31]
	v_mfma_f32_16x16x32_f16 v[24:27], v[176:179], v[200:203], v[24:27]
	v_mfma_f32_16x16x32_f16 v[12:15], v[168:171], v[208:211], v[12:15]
	v_mfma_f32_16x16x32_f16 v[8:11], v[176:179], v[208:211], v[8:11]
	s_setprio 0
	s_barrier
; #define PG8_STAGE(bufoff, gbase, voff) do { _Pragma("unroll") for (int _i = 0; _i < 2; ++_i) \
;         __builtin_amdgcn_global_load_lds((const unsigned*)((const char*)(gbase) + (voff)[_i]), (LAS unsigned*)(lds + (bufoff) + ldsw + _i * 8192), 16, 0, 0); } while (0)
; #define PG8_LDA(dst, b, h) do { _Pragma("unroll") for (int m = 0; m < 4; ++m) _Pragma("unroll") for (int k = 0; k < 2; ++k) dst[m][k] = *(const LAS h16x8*)(lds + PG8_SA(b, h) + aoff + m * 2048 + k * 1024); } while (0)
; #define PG8_LDB(dst, b, h) do { _Pragma("unroll") for (int n = 0; n < 2; ++n) _Pragma("unroll") for (int k = 0; k < 2; ++k) dst[n][k] = *(const LAS h16x8*)(lds + PG8_SB(b, h) + boff + n * 2048 + k * 1024); } while (0)
; #define PG8_MMA(ai, bj, At, Bt) do { __builtin_amdgcn_s_setprio(1); _Pragma("unroll") for (int m = 0; m < 4; ++m) _Pragma("unroll") for (int n = 0; n < 2; ++n) _Pragma("unroll") for (int k = 0; k < 2; ++k) \
;         acc[ai][bj][m][n] = __builtin_amdgcn_mfma_f32_16x16x32_f16(Bt[n][k], At[m][k], acc[ai][bj][m][n], 0, 0, 0); __builtin_amdgcn_s_setprio(0); } while (0)
; #define PG8_WAIT_V(n) asm volatile("s_waitcnt vmcnt(" #n ")" ::: "memory")
; #define PG8_WAIT_L(n) asm volatile("s_waitcnt lgkmcnt(" #n ")" ::: "memory")
; #define PG8_BAR __builtin_amdgcn_s_barrier()
; #define PG8_SCHED __builtin_amdgcn_sched_barrier(0)
; template <class Epi>
; __device__ __forceinline__ void gemm_phase(LAS unsigned char* lds, const Gemm g, const StaticOrder& S, const Epi& E) {
;     ...
;             PG8_WAIT_V(6); PG8_BAR; PG8_MMA(1, 1, At, B1); PG8_BAR;
;             PG8_LDB(B0, 1, 0); PG8_SCHED; PG8_LDA(At, 1, 0); PG8_STAGE(PG8_SA(0, 1), a2 + hstep, voffA);
;             PG8_WAIT_L(8); PG8_BAR; PG8_WAIT_L(0); PG8_MMA(0, 0, At, B0); PG8_BAR; PG8_SCHED;
;             PG8_LDB(B1, 1, 1); PG8_STAGE(PG8_SB(1, 0), b3, voffB);
;             PG8_BAR; PG8_WAIT_L(0); PG8_MMA(0, 1, At, B1); PG8_BAR;
;             PG8_LDA(At, 1, 1); PG8_STAGE(PG8_SA(1, 0), a3, voffA);
;             PG8_BAR; PG8_WAIT_L(0); PG8_MMA(1, 0, At, B0); PG8_BAR; PG8_SCHED;
	s_add_u32 s52, s28, 0x40000
	s_addc_u32 s53, s29, 0
	s_add_i32 s51, s46, s37
	v_lshl_add_u64 v[162:163], s[52:53], 0, v[148:149]
	s_mov_b32 m0, s51
	s_nop 0
	global_load_lds_dwordx4 v[162:163], off
	v_lshl_add_u64 v[162:163], s[52:53], 0, v[152:153]
	s_add_i32 m0, s51, 0x2000
	s_nop 0
	global_load_lds_dwordx4 v[162:163], off
	s_waitcnt vmcnt(6)
	s_barrier
	s_setprio 1
	v_mfma_f32_16x16x32_f16 v[52:55], v[212:215], v[180:183], v[52:55]
	v_mfma_f32_16x16x32_f16 v[48:51], v[220:223], v[180:183], v[48:51]
	v_mfma_f32_16x16x32_f16 v[36:39], v[212:215], v[188:191], v[36:39]
	v_mfma_f32_16x16x32_f16 v[32:35], v[220:223], v[188:191], v[32:35]
	v_mfma_f32_16x16x32_f16 v[20:23], v[212:215], v[196:199], v[20:23]
	v_mfma_f32_16x16x32_f16 v[16:19], v[220:223], v[196:199], v[16:19]
	v_mfma_f32_16x16x32_f16 v[4:7], v[212:215], v[204:207], v[4:7]
	v_mfma_f32_16x16x32_f16 v[0:3], v[220:223], v[204:207], v[0:3]
	v_mfma_f32_16x16x32_f16 v[52:55], v[216:219], v[184:187], v[52:55]
	v_mfma_f32_16x16x32_f16 v[48:51], v[224:227], v[184:187], v[48:51]
	v_mfma_f32_16x16x32_f16 v[36:39], v[216:219], v[192:195], v[36:39]
	v_mfma_f32_16x16x32_f16 v[32:35], v[224:227], v[192:195], v[32:35]
	v_mfma_f32_16x16x32_f16 v[20:23], v[216:219], v[200:203], v[20:23]
	v_mfma_f32_16x16x32_f16 v[16:19], v[224:227], v[200:203], v[16:19]
	v_mfma_f32_16x16x32_f16 v[4:7], v[216:219], v[208:211], v[4:7]
	v_mfma_f32_16x16x32_f16 v[0:3], v[224:227], v[208:211], v[0:3]
	s_setprio 0
	s_add_i32 s51, 0, 0x18000
	v_add_u32_e32 v167, s51, v139
	s_barrier
	ds_read_b128 v[162:165], v167
	ds_read_b128 v[168:171], v167 offset:1024
	ds_read_b128 v[172:175], v167 offset:2048
	ds_read_b128 v[176:179], v167 offset:3072
	s_add_u32 s30, s30, 0x40000
	s_addc_u32 s31, s31, 0
	s_mov_b32 m0, s39
	v_lshl_add_u64 v[212:213], s[30:31], 0, v[142:143]
	ds_read_b128 v[180:183], v147 offset:32768
	ds_read_b128 v[184:187], v147 offset:33792
	ds_read_b128 v[188:191], v147 offset:34816
	ds_read_b128 v[192:195], v147 offset:35840
	ds_read_b128 v[196:199], v147 offset:36864
	ds_read_b128 v[200:203], v147 offset:37888
	ds_read_b128 v[204:207], v147 offset:38912
	ds_read_b128 v[208:211], v147 offset:39936
	global_load_lds_dwordx4 v[212:213], off
	v_lshl_add_u64 v[212:213], s[30:31], 0, v[150:151]
	s_mov_b32 m0, s41
	s_nop 0
	global_load_lds_dwordx4 v[212:213], off
	s_waitcnt lgkmcnt(8)
	s_barrier
	s_waitcnt lgkmcnt(0)
	s_setprio 1
	s_waitcnt lgkmcnt(0)
	v_mfma_f32_16x16x32_f16 v[124:127], v[162:165], v[180:183], v[124:127]
	v_mfma_f32_16x16x32_f16 v[120:123], v[172:175], v[180:183], v[120:123]
	v_mfma_f32_16x16x32_f16 v[108:111], v[162:165], v[188:191], v[108:111]
	v_mfma_f32_16x16x32_f16 v[104:107], v[172:175], v[188:191], v[104:107]
	v_mfma_f32_16x16x32_f16 v[92:95], v[162:165], v[196:199], v[92:95]
	v_mfma_f32_16x16x32_f16 v[88:91], v[172:175], v[196:199], v[88:91]
	v_mfma_f32_16x16x32_f16 v[76:79], v[162:165], v[204:207], v[76:79]
	v_mfma_f32_16x16x32_f16 v[72:75], v[172:175], v[204:207], v[72:75]
	v_mfma_f32_16x16x32_f16 v[124:127], v[168:171], v[184:187], v[124:127]
	v_mfma_f32_16x16x32_f16 v[120:123], v[176:179], v[184:187], v[120:123]
	v_mfma_f32_16x16x32_f16 v[108:111], v[168:171], v[192:195], v[108:111]
	v_mfma_f32_16x16x32_f16 v[104:107], v[176:179], v[192:195], v[104:107]
	v_mfma_f32_16x16x32_f16 v[92:95], v[168:171], v[200:203], v[92:95]
	v_mfma_f32_16x16x32_f16 v[88:91], v[176:179], v[200:203], v[88:91]
	v_mfma_f32_16x16x32_f16 v[76:79], v[168:171], v[208:211], v[76:79]
	v_mfma_f32_16x16x32_f16 v[72:75], v[176:179], v[208:211], v[72:75]
	s_setprio 0
	s_barrier
	s_add_i32 s30, 0, 0x1c000
	s_add_i32 s31, s51, s37
	v_add_u32_e32 v167, s30, v139
	v_lshl_add_u64 v[228:229], v[228:229], 0, s[0:1]
	s_mov_b32 m0, s31
	ds_read_b128 v[212:215], v167
	ds_read_b128 v[216:219], v167 offset:1024
	ds_read_b128 v[220:223], v167 offset:2048
	ds_read_b128 v[224:227], v167 offset:3072
	global_load_lds_dwordx4 v[228:229], off
	v_lshl_add_u64 v[228:229], v[230:231], 0, s[0:1]
	s_add_i32 m0, s31, 0x2000
	s_nop 0
	global_load_lds_dwordx4 v[228:229], off
	s_barrier
	s_waitcnt lgkmcnt(0)
	s_setprio 1
	s_waitcnt lgkmcnt(0)
	v_mfma_f32_16x16x32_f16 v[116:119], v[212:215], v[180:183], v[116:119]
	v_mfma_f32_16x16x32_f16 v[112:115], v[220:223], v[180:183], v[112:115]
	v_mfma_f32_16x16x32_f16 v[100:103], v[212:215], v[188:191], v[100:103]
	v_mfma_f32_16x16x32_f16 v[96:99], v[220:223], v[188:191], v[96:99]
	v_mfma_f32_16x16x32_f16 v[84:87], v[212:215], v[196:199], v[84:87]
	v_mfma_f32_16x16x32_f16 v[80:83], v[220:223], v[196:199], v[80:83]
	v_mfma_f32_16x16x32_f16 v[68:71], v[212:215], v[204:207], v[68:71]
	v_mfma_f32_16x16x32_f16 v[64:67], v[220:223], v[204:207], v[64:67]
	v_mfma_f32_16x16x32_f16 v[116:119], v[216:219], v[184:187], v[116:119]
	v_mfma_f32_16x16x32_f16 v[112:115], v[224:227], v[184:187], v[112:115]
	v_mfma_f32_16x16x32_f16 v[100:103], v[216:219], v[192:195], v[100:103]
	v_mfma_f32_16x16x32_f16 v[96:99], v[224:227], v[192:195], v[96:99]
	v_mfma_f32_16x16x32_f16 v[84:87], v[216:219], v[200:203], v[84:87]
	v_mfma_f32_16x16x32_f16 v[80:83], v[224:227], v[200:203], v[80:83]
	v_mfma_f32_16x16x32_f16 v[68:71], v[216:219], v[208:211], v[68:71]
	v_mfma_f32_16x16x32_f16 v[64:67], v[224:227], v[208:211], v[64:67]
	s_setprio 0
	s_mov_b32 m0, s43
	v_lshl_add_u64 v[228:229], v[232:233], 0, s[0:1]
	s_barrier
	ds_read_b128 v[180:183], v147 offset:49152
	ds_read_b128 v[184:187], v147 offset:50176
	ds_read_b128 v[188:191], v147 offset:51200
	ds_read_b128 v[192:195], v147 offset:52224
	ds_read_b128 v[196:199], v147 offset:53248
	ds_read_b128 v[200:203], v147 offset:54272
	ds_read_b128 v[204:207], v147 offset:55296
	ds_read_b128 v[208:211], v147 offset:56320
	global_load_lds_dwordx4 v[228:229], off
	v_lshl_add_u64 v[228:229], v[234:235], 0, s[0:1]
	s_mov_b32 m0, s44
	s_nop 0
	global_load_lds_dwordx4 v[228:229], off
	s_barrier
; template <class Epi>
; __device__ __forceinline__ void gemm_phase(LAS unsigned char* lds, const Gemm g, const StaticOrder& S, const Epi& E) {
;     ...
;             PG8_BAR; PG8_WAIT_L(0); PG8_MMA(1, 0, At, B0); PG8_BAR; PG8_SCHED;
;             PG8_STAGE(PG8_SB(1, 1), b3 + hstep, voffB);
;             PG8_WAIT_V(6); PG8_BAR; PG8_MMA(1, 1, At, B1); PG8_BAR;
;         }
;     __device__ __forceinline__ void operator()(const f32x4 (&acc)[2][2][4][2], const pg8::Unit& u, int wr, int wc, int fr, int fq) const {
;         const int row0 = u.pm * 256 + wr * 64 + fr, col0 = u.pn * 256 + wc * 32 + 8 * fq;
; #pragma unroll
;         for (int ai = 0; ai < 2; ++ai)
; #pragma unroll
;             for (int m = 0; m < 4; ++m) {
;                 const int row = row0 + ai * 128 + m * 16;
;                 float ss = 0.f, rstd = 1.f;
;                 if (MODE == 2) rstd = rsqrtf(rowss[row] * (1.f / 1024.f) + EPS);
; #pragma unroll
;                 for (int bj = 0; bj < 2; ++bj) {
;                     const int c = col0 + bj * 128;
;                     f32x4 v0 = acc[ai][bj][m][0], v1 = acc[ai][bj][m][1];
;                     if (MODE == 1) {
;                         const float* rp = res + (size_t)row * ldres + c;
;                         v0 += *(const f32x4*)rp; v1 += *(const f32x4*)(rp + 4);
;                     }
;                     if (MODE == 3) {
;                         const h16x8 r8 = *(const h16x8*)(res16 + (size_t)row * ldres + c);
; #pragma unroll
;                         for (int j = 0; j < 4; ++j) { v0[j] += (float)r8[j]; v1[j] += (float)r8[4 + j]; }
;                     }
;                     if (MODE == 1 || MODE == 3) {
;                         ss += v0[0] * v0[0] + v0[1] * v0[1] + v0[2] * v0[2] + v0[3] * v0[3] + v1[0] * v1[0] + v1[1] * v1[1] + v1[2] * v1[2] + v1[3] * v1[3];
;                     }
;                     if (MODE == 2) {
; #pragma unroll
;                         for (int j = 0; j < 4; ++j) { float a = fmaxf(v0[j] * rstd, 0.f), b = fmaxf(v1[j] * rstd, 0.f); v0[j] = a * a; v1[j] = b * b; }
;                     }
;                     *(h16x8*)(o16 + (size_t)row * ld16 + c) = pack8(v0, v1);
;                 }
;                 if (MODE == 1 || MODE == 3) {
;                     ss += __shfl_xor(ss, 16); ss += __shfl_xor(ss, 32);
;                     if (fq == 0) atomicAdd(rowss + row, ss);
	s_waitcnt lgkmcnt(0)
	s_setprio 1
	s_waitcnt lgkmcnt(0)
	v_mfma_f32_16x16x32_f16 v[60:63], v[162:165], v[180:183], v[60:63]
	v_mfma_f32_16x16x32_f16 v[56:59], v[172:175], v[180:183], v[56:59]
	v_mfma_f32_16x16x32_f16 v[44:47], v[162:165], v[188:191], v[44:47]
	v_mfma_f32_16x16x32_f16 v[40:43], v[172:175], v[188:191], v[40:43]
	v_mfma_f32_16x16x32_f16 v[28:31], v[162:165], v[196:199], v[28:31]
	v_mfma_f32_16x16x32_f16 v[24:27], v[172:175], v[196:199], v[24:27]
	v_mfma_f32_16x16x32_f16 v[12:15], v[162:165], v[204:207], v[12:15]
	v_mfma_f32_16x16x32_f16 v[8:11], v[172:175], v[204:207], v[8:11]
	v_mfma_f32_16x16x32_f16 v[60:63], v[168:171], v[184:187], v[60:63]
	v_mfma_f32_16x16x32_f16 v[56:59], v[176:179], v[184:187], v[56:59]
	v_mfma_f32_16x16x32_f16 v[44:47], v[168:171], v[192:195], v[44:47]
	v_mfma_f32_16x16x32_f16 v[40:43], v[176:179], v[192:195], v[40:43]
	v_mfma_f32_16x16x32_f16 v[28:31], v[168:171], v[200:203], v[28:31]
	v_mfma_f32_16x16x32_f16 v[24:27], v[176:179], v[200:203], v[24:27]
	v_mfma_f32_16x16x32_f16 v[12:15], v[168:171], v[208:211], v[12:15]
	v_mfma_f32_16x16x32_f16 v[8:11], v[176:179], v[208:211], v[8:11]
	s_setprio 0
	s_barrier
	s_add_u32 s28, s28, 0x40080
	s_addc_u32 s29, s29, 0
	s_add_i32 s30, s30, s37
	v_lshl_add_u64 v[162:163], s[28:29], 0, v[148:149]
	s_mov_b32 m0, s30
	s_nop 0
	global_load_lds_dwordx4 v[162:163], off
	v_lshl_add_u64 v[162:163], s[28:29], 0, v[152:153]
	s_add_i32 m0, s30, 0x2000
	s_nop 0
	global_load_lds_dwordx4 v[162:163], off
	s_waitcnt vmcnt(6)
	s_barrier
	s_setprio 1
	v_mfma_f32_16x16x32_f16 v[52:55], v[212:215], v[180:183], v[52:55]
	v_mfma_f32_16x16x32_f16 v[48:51], v[220:223], v[180:183], v[48:51]
	v_mfma_f32_16x16x32_f16 v[36:39], v[212:215], v[188:191], v[36:39]
	v_mfma_f32_16x16x32_f16 v[32:35], v[220:223], v[188:191], v[32:35]
	v_mfma_f32_16x16x32_f16 v[20:23], v[212:215], v[196:199], v[20:23]
	v_mfma_f32_16x16x32_f16 v[16:19], v[220:223], v[196:199], v[16:19]
	v_mfma_f32_16x16x32_f16 v[4:7], v[212:215], v[204:207], v[4:7]
	v_mfma_f32_16x16x32_f16 v[0:3], v[220:223], v[204:207], v[0:3]
	v_mfma_f32_16x16x32_f16 v[52:55], v[216:219], v[184:187], v[52:55]
	v_mfma_f32_16x16x32_f16 v[48:51], v[224:227], v[184:187], v[48:51]
	v_mfma_f32_16x16x32_f16 v[36:39], v[216:219], v[192:195], v[36:39]
	v_mfma_f32_16x16x32_f16 v[32:35], v[224:227], v[192:195], v[32:35]
	v_mfma_f32_16x16x32_f16 v[20:23], v[216:219], v[200:203], v[20:23]
	v_mfma_f32_16x16x32_f16 v[16:19], v[224:227], v[200:203], v[16:19]
	v_mfma_f32_16x16x32_f16 v[4:7], v[216:219], v[208:211], v[4:7]
	v_mfma_f32_16x16x32_f16 v[0:3], v[224:227], v[208:211], v[0:3]
	s_setprio 0
	s_add_i32 s50, s50, 2
	s_add_u32 s26, s26, 0x100
	s_addc_u32 s27, s27, 0
	s_add_u32 s48, s48, 0x100
	s_addc_u32 s49, s49, 0
	s_cmp_gt_u32 s50, 13
	s_barrier
	s_cbranch_scc0 .LBB0_422
	v_lshl_add_u32 v164, s22, 8, v137
	v_ashrrev_i32_e32 v165, 31, v164
	v_readlane_b32 s48, v253, 4
	v_lshl_or_b32 v162, s24, 8, v141
	v_lshlrev_b64 v[168:169], 12, v[164:165]
	v_readlane_b32 s49, v253, 5
	v_ashrrev_i32_e32 v163, 31, v162
	v_lshlrev_b64 v[178:179], 11, v[164:165]
	v_lshl_add_u64 v[168:169], s[48:49], 0, v[168:169]
	v_lshl_add_u64 v[176:177], v[162:163], 2, v[168:169]
	global_load_dwordx4 v[168:171], v[176:177], off
	global_load_dwordx4 v[172:175], v[176:177], off offset:16
	v_lshlrev_b32_e32 v182, 12, v164
	v_lshl_add_u32 v182, v162, 2, v182
	v_add_u32_e32 v183, 0x80000, v182
	global_load_dword v184, v182, s[48:49] offset:512
	v_add_u32_e32 v185, 0x10000, v182
	global_load_dword v186, v185, s[48:49]
	global_load_dword v187, v185, s[48:49] offset:512
	v_add_u32_e32 v188, 0x20000, v182
	global_load_dword v189, v188, s[48:49]
	global_load_dword v190, v188, s[48:49] offset:512
	v_add_u32_e32 v191, 0x30000, v182
	global_load_dword v192, v191, s[48:49]
	global_load_dword v193, v191, s[48:49] offset:512
	global_load_dword v194, v183, s[48:49]
	global_load_dword v195, v183, s[48:49] offset:512
	v_add_u32_e32 v196, 0x10000, v183
	global_load_dword v197, v196, s[48:49]
	global_load_dword v198, v196, s[48:49] offset:512
	v_add_u32_e32 v199, 0x20000, v183
	global_load_dword v200, v199, s[48:49]
	global_load_dword v201, v199, s[48:49] offset:512
	v_add_u32_e32 v202, 0x30000, v183
	global_load_dword v204, v202, s[48:49]
	global_load_dword v205, v202, s[48:49] offset:512
	v_lshl_add_u64 v[178:179], s[10:11], 0, v[178:179]
	v_lshl_add_u64 v[178:179], v[162:163], 1, v[178:179]
	v_readlane_b32 s50, v253, 6
	v_readlane_b32 s51, v253, 7
	v_readlane_b32 s52, v253, 8
	v_readlane_b32 s53, v253, 9
	v_readlane_b32 s54, v253, 10
	v_readlane_b32 s55, v253, 11
	v_readlane_b32 s56, v253, 12
	v_readlane_b32 s57, v253, 13
	v_readlane_b32 s58, v253, 14
	v_readlane_b32 s59, v253, 15
	v_readlane_b32 s60, v253, 16
	v_readlane_b32 s61, v253, 17
	v_readlane_b32 s62, v253, 18
	v_readlane_b32 s63, v253, 19
	s_waitcnt vmcnt(0)
	v_pk_add_f32 v[126:127], v[126:127], v[170:171]
	v_pk_add_f32 v[180:181], v[124:125], v[168:169]
	v_pk_add_f32 v[174:175], v[122:123], v[174:175]
	v_pk_add_f32 v[172:173], v[120:121], v[172:173]
	v_cvt_pk_f16_f32 v123, v174, v175
	v_cvt_pk_f16_f32 v121, v126, v127
	v_cvt_pk_f16_f32 v122, v172, v173
	v_cvt_pk_f16_f32 v120, v180, v181
	global_store_dwordx4 v[178:179], v[120:123], off
	global_load_dwordx4 v[122:125], v[176:177], off offset:512
	s_nop 0
	global_load_dwordx4 v[168:171], v[176:177], off offset:528
	v_mul_f32_e32 v167, v181, v181
	v_fmac_f32_e32 v167, v180, v180
	v_fmac_f32_e32 v167, v126, v126
	v_fmac_f32_e32 v167, v127, v127
	v_fmac_f32_e32 v167, v172, v172
	v_xor_b32_e32 v120, 16, v129
	v_fmac_f32_e32 v167, v173, v173
	v_cmp_lt_i32_e32 vcc, v120, v135
	v_fmac_f32_e32 v167, v174, v174
	v_fmac_f32_e32 v167, v175, v175
	v_cndmask_b32_e32 v120, v129, v120, vcc
	v_lshlrev_b32_e32 v120, 2, v120
	v_xor_b32_e32 v121, 32, v129
	v_cmp_lt_i32_e32 vcc, v121, v135
	s_waitcnt vmcnt(0)
	v_pk_add_f32 v[122:123], v[116:117], v[122:123]
	v_pk_add_f32 v[126:127], v[112:113], v[168:169]
	v_mul_f32_e32 v112, v123, v123
	v_pk_add_f32 v[124:125], v[118:119], v[124:125]
	v_fmac_f32_e32 v112, v122, v122
	v_fmac_f32_e32 v112, v124, v124
	v_fmac_f32_e32 v112, v125, v125
	v_fmac_f32_e32 v112, v126, v126
	v_pk_add_f32 v[116:117], v[114:115], v[170:171]
	v_fmac_f32_e32 v112, v127, v127
	v_fmac_f32_e32 v112, v116, v116
	v_fmac_f32_e32 v112, v117, v117
	v_add_f32_e32 v112, v167, v112
	ds_bpermute_b32 v113, v120, v112
	v_cndmask_b32_e32 v114, v129, v121, vcc
	v_lshlrev_b32_e32 v114, 2, v114
	v_cvt_pk_f16_f32 v119, v116, v117
	v_cvt_pk_f16_f32 v117, v124, v125
	s_waitcnt lgkmcnt(0)
	v_add_f32_e32 v112, v112, v113
	ds_bpermute_b32 v113, v114, v112
	v_cvt_pk_f16_f32 v118, v126, v127
	v_cvt_pk_f16_f32 v116, v122, v123
	global_store_dwordx4 v[178:179], v[116:119], off offset:256
	s_and_saveexec_b64 s[22:23], s[6:7]
	s_cbranch_execz .LBB0_425
	v_lshl_add_u64 v[116:117], v[164:165], 2, s[14:15]
	s_waitcnt lgkmcnt(0)
	v_add_f32_e32 v112, v112, v113
	global_atomic_add_f32 v[116:117], v112, off

; #define PG8_STAGE(bufoff, gbase, voff) do { _Pragma("unroll") for (int _i = 0; _i < 2; ++_i) \
;         __builtin_amdgcn_global_load_lds((const unsigned*)((const char*)(gbase) + (voff)[_i]), (LAS unsigned*)(lds + (bufoff) + ldsw + _i * 8192), 16, 0, 0); } while (0)
; #define PG8_LDA(dst, b, h) do { _Pragma("unroll") for (int m = 0; m < 4; ++m) _Pragma("unroll") for (int k = 0; k < 2; ++k) dst[m][k] = *(const LAS h16x8*)(lds + PG8_SA(b, h) + aoff + m * 2048 + k * 1024); } while (0)
; #define PG8_LDB(dst, b, h) do { _Pragma("unroll") for (int n = 0; n < 2; ++n) _Pragma("unroll") for (int k = 0; k < 2; ++k) dst[n][k] = *(const LAS h16x8*)(lds + PG8_SB(b, h) + boff + n * 2048 + k * 1024); } while (0)
; #define PG8_MMA(ai, bj, At, Bt) do { __builtin_amdgcn_s_setprio(1); _Pragma("unroll") for (int m = 0; m < 4; ++m) _Pragma("unroll") for (int n = 0; n < 2; ++n) _Pragma("unroll") for (int k = 0; k < 2; ++k) \
;         acc[ai][bj][m][n] = __builtin_amdgcn_mfma_f32_16x16x32_f16(Bt[n][k], At[m][k], acc[ai][bj][m][n], 0, 0, 0); __builtin_amdgcn_s_setprio(0); } while (0)
; #define PG8_WAIT_V(n) asm volatile("s_waitcnt vmcnt(" #n ")" ::: "memory")
; #define PG8_WAIT_L(n) asm volatile("s_waitcnt lgkmcnt(" #n ")" ::: "memory")
; #define PG8_BAR __builtin_amdgcn_s_barrier()
; #define PG8_SCHED __builtin_amdgcn_sched_barrier(0)
; template <class Epi>
; __device__ __forceinline__ void gemm_phase(LAS unsigned char* lds, const Gemm g, const StaticOrder& S, const Epi& E) {
;     ...
;             PG8_LDB(B0, 0, 0); PG8_SCHED; PG8_LDA(At, 0, 0); PG8_STAGE(PG8_SA(1, 1), a1 + hstep, voffA);
;             PG8_WAIT_L(8); PG8_BAR; PG8_WAIT_L(0); PG8_MMA(0, 0, At, B0); PG8_BAR; PG8_SCHED;
;             PG8_LDB(B1, 0, 1); PG8_STAGE(PG8_SB(0, 0), b2, voffB);
;             PG8_BAR; PG8_WAIT_L(0); PG8_MMA(0, 1, At, B1); PG8_BAR;
;             PG8_LDA(At, 0, 1); PG8_STAGE(PG8_SA(0, 0), a2, voffA);
;             PG8_BAR; PG8_WAIT_L(0); PG8_MMA(1, 0, At, B0); PG8_BAR; PG8_SCHED;
;             PG8_STAGE(PG8_SB(0, 1), b2 + hstep, voffB);
;             PG8_WAIT_V(6); PG8_BAR; PG8_MMA(1, 1, At, B1); PG8_BAR;
.LBB0_483:
	ds_read_b128 v[160:163], v168
	ds_read_b128 v[164:167], v168 offset:1024
	ds_read_b128 v[172:175], v168 offset:2048
	ds_read_b128 v[176:179], v168 offset:3072
	s_add_u32 s36, s0, 0xfffc0080
	s_addc_u32 s37, s1, -1
	s_cmp_eq_u32 s63, 12
	s_cselect_b32 s39, s27, s37
	s_cselect_b32 s38, s59, s36
	s_cselect_b32 s37, s25, s62
	s_cselect_b32 s36, s60, s61
	v_lshl_add_u64 v[212:213], s[0:1], 0, v[152:153]
	s_add_i32 m0, s35, 0xc000
	ds_read_b128 v[180:183], v169
	ds_read_b128 v[184:187], v169 offset:1024
	ds_read_b128 v[188:191], v169 offset:2048
	ds_read_b128 v[192:195], v169 offset:3072
	ds_read_b128 v[196:199], v169 offset:4096
	ds_read_b128 v[200:203], v169 offset:5120
	ds_read_b128 v[204:207], v169 offset:6144
	ds_read_b128 v[208:211], v169 offset:7168
	global_load_lds_dwordx4 v[212:213], off
	v_lshl_add_u64 v[212:213], s[0:1], 0, v[154:155]
	s_add_i32 m0, s35, 0xe000
	s_nop 0
	global_load_lds_dwordx4 v[212:213], off
	s_waitcnt lgkmcnt(8)
	s_barrier
	s_waitcnt lgkmcnt(0)
	s_setprio 1
	s_waitcnt lgkmcnt(0)
	v_mfma_f32_16x16x32_f16 v[124:127], v[160:163], v[180:183], v[124:127]
	v_mfma_f32_16x16x32_f16 v[120:123], v[172:175], v[180:183], v[120:123]
	v_mfma_f32_16x16x32_f16 v[108:111], v[160:163], v[188:191], v[108:111]
	v_mfma_f32_16x16x32_f16 v[104:107], v[172:175], v[188:191], v[104:107]
	v_mfma_f32_16x16x32_f16 v[92:95], v[160:163], v[196:199], v[92:95]
	v_mfma_f32_16x16x32_f16 v[88:91], v[172:175], v[196:199], v[88:91]
	v_mfma_f32_16x16x32_f16 v[76:79], v[160:163], v[204:207], v[76:79]
	v_mfma_f32_16x16x32_f16 v[72:75], v[172:175], v[204:207], v[72:75]
	v_mfma_f32_16x16x32_f16 v[124:127], v[164:167], v[184:187], v[124:127]
	v_mfma_f32_16x16x32_f16 v[120:123], v[176:179], v[184:187], v[120:123]
	v_mfma_f32_16x16x32_f16 v[108:111], v[164:167], v[192:195], v[108:111]
	v_mfma_f32_16x16x32_f16 v[104:107], v[176:179], v[192:195], v[104:107]
	v_mfma_f32_16x16x32_f16 v[92:95], v[164:167], v[200:203], v[92:95]
	v_mfma_f32_16x16x32_f16 v[88:91], v[176:179], v[200:203], v[88:91]
	v_mfma_f32_16x16x32_f16 v[76:79], v[164:167], v[208:211], v[76:79]
	v_mfma_f32_16x16x32_f16 v[72:75], v[176:179], v[208:211], v[72:75]
	s_setprio 0
	s_barrier
	s_add_i32 s64, s51, s44
	v_lshl_add_u64 v[228:229], s[36:37], 0, v[144:145]
	s_mov_b32 m0, s64
	ds_read_b128 v[212:215], v170
	ds_read_b128 v[216:219], v170 offset:1024
	ds_read_b128 v[220:223], v170 offset:2048
	ds_read_b128 v[224:227], v170 offset:3072
	global_load_lds_dwordx4 v[228:229], off
	v_lshl_add_u64 v[230:231], s[36:37], 0, v[150:151]
	s_add_i32 m0, s64, 0x2000
	s_nop 0
	global_load_lds_dwordx4 v[230:231], off
	s_barrier
	s_waitcnt lgkmcnt(0)
	s_setprio 1
	s_waitcnt lgkmcnt(0)
	v_mfma_f32_16x16x32_f16 v[116:119], v[212:215], v[180:183], v[116:119]
	v_mfma_f32_16x16x32_f16 v[112:115], v[220:223], v[180:183], v[112:115]
	v_mfma_f32_16x16x32_f16 v[100:103], v[212:215], v[188:191], v[100:103]
	v_mfma_f32_16x16x32_f16 v[96:99], v[220:223], v[188:191], v[96:99]
	v_mfma_f32_16x16x32_f16 v[84:87], v[212:215], v[196:199], v[84:87]
	v_mfma_f32_16x16x32_f16 v[80:83], v[220:223], v[196:199], v[80:83]
	v_mfma_f32_16x16x32_f16 v[68:71], v[212:215], v[204:207], v[68:71]
	v_mfma_f32_16x16x32_f16 v[64:67], v[220:223], v[204:207], v[64:67]
	v_mfma_f32_16x16x32_f16 v[116:119], v[216:219], v[184:187], v[116:119]
	v_mfma_f32_16x16x32_f16 v[112:115], v[224:227], v[184:187], v[112:115]
	v_mfma_f32_16x16x32_f16 v[100:103], v[216:219], v[192:195], v[100:103]
	v_mfma_f32_16x16x32_f16 v[96:99], v[224:227], v[192:195], v[96:99]
	v_mfma_f32_16x16x32_f16 v[84:87], v[216:219], v[200:203], v[84:87]
	v_mfma_f32_16x16x32_f16 v[80:83], v[224:227], v[200:203], v[80:83]
	v_mfma_f32_16x16x32_f16 v[68:71], v[216:219], v[208:211], v[68:71]
	v_mfma_f32_16x16x32_f16 v[64:67], v[224:227], v[208:211], v[64:67]
	s_setprio 0
	s_mov_b32 m0, s35
	v_lshl_add_u64 v[232:233], s[38:39], 0, v[142:143]
	s_barrier
	ds_read_b128 v[180:183], v169 offset:16384
	ds_read_b128 v[184:187], v169 offset:17408
	ds_read_b128 v[188:191], v169 offset:18432
	ds_read_b128 v[192:195], v169 offset:19456
	ds_read_b128 v[196:199], v169 offset:20480
	ds_read_b128 v[200:203], v169 offset:21504
	ds_read_b128 v[204:207], v169 offset:22528
	ds_read_b128 v[208:211], v169 offset:23552
	global_load_lds_dwordx4 v[232:233], off
	v_lshl_add_u64 v[234:235], s[38:39], 0, v[148:149]
	s_mov_b32 m0, s45
	s_nop 0
	global_load_lds_dwordx4 v[234:235], off
	s_barrier
	s_waitcnt lgkmcnt(0)
	s_setprio 1
	s_waitcnt lgkmcnt(0)
	v_mfma_f32_16x16x32_f16 v[60:63], v[160:163], v[180:183], v[60:63]
	v_mfma_f32_16x16x32_f16 v[56:59], v[172:175], v[180:183], v[56:59]
	v_mfma_f32_16x16x32_f16 v[44:47], v[160:163], v[188:191], v[44:47]
	v_mfma_f32_16x16x32_f16 v[40:43], v[172:175], v[188:191], v[40:43]
	v_mfma_f32_16x16x32_f16 v[28:31], v[160:163], v[196:199], v[28:31]
	v_mfma_f32_16x16x32_f16 v[24:27], v[172:175], v[196:199], v[24:27]
	v_mfma_f32_16x16x32_f16 v[12:15], v[160:163], v[204:207], v[12:15]
	v_mfma_f32_16x16x32_f16 v[8:11], v[172:175], v[204:207], v[8:11]
	v_mfma_f32_16x16x32_f16 v[60:63], v[164:167], v[184:187], v[60:63]
	v_mfma_f32_16x16x32_f16 v[56:59], v[176:179], v[184:187], v[56:59]
	v_mfma_f32_16x16x32_f16 v[44:47], v[164:167], v[192:195], v[44:47]
	v_mfma_f32_16x16x32_f16 v[40:43], v[176:179], v[192:195], v[40:43]
	v_mfma_f32_16x16x32_f16 v[28:31], v[164:167], v[200:203], v[28:31]
	v_mfma_f32_16x16x32_f16 v[24:27], v[176:179], v[200:203], v[24:27]
	v_mfma_f32_16x16x32_f16 v[12:15], v[164:167], v[208:211], v[12:15]
	v_mfma_f32_16x16x32_f16 v[8:11], v[176:179], v[208:211], v[8:11]
	s_setprio 0
	s_barrier
; #define PG8_STAGE(bufoff, gbase, voff) do { _Pragma("unroll") for (int _i = 0; _i < 2; ++_i) \
;         __builtin_amdgcn_global_load_lds((const unsigned*)((const char*)(gbase) + (voff)[_i]), (LAS unsigned*)(lds + (bufoff) + ldsw + _i * 8192), 16, 0, 0); } while (0)
; #define PG8_LDA(dst, b, h) do { _Pragma("unroll") for (int m = 0; m < 4; ++m) _Pragma("unroll") for (int k = 0; k < 2; ++k) dst[m][k] = *(const LAS h16x8*)(lds + PG8_SA(b, h) + aoff + m * 2048 + k * 1024); } while (0)
; #define PG8_LDB(dst, b, h) do { _Pragma("unroll") for (int n = 0; n < 2; ++n) _Pragma("unroll") for (int k = 0; k < 2; ++k) dst[n][k] = *(const LAS h16x8*)(lds + PG8_SB(b, h) + boff + n * 2048 + k * 1024); } while (0)
; #define PG8_MMA(ai, bj, At, Bt) do { __builtin_amdgcn_s_setprio(1); _Pragma("unroll") for (int m = 0; m < 4; ++m) _Pragma("unroll") for (int n = 0; n < 2; ++n) _Pragma("unroll") for (int k = 0; k < 2; ++k) \
;         acc[ai][bj][m][n] = __builtin_amdgcn_mfma_f32_16x16x32_f16(Bt[n][k], At[m][k], acc[ai][bj][m][n], 0, 0, 0); __builtin_amdgcn_s_setprio(0); } while (0)
; #define PG8_WAIT_V(n) asm volatile("s_waitcnt vmcnt(" #n ")" ::: "memory")
; #define PG8_WAIT_L(n) asm volatile("s_waitcnt lgkmcnt(" #n ")" ::: "memory")
; #define PG8_BAR __builtin_amdgcn_s_barrier()
; #define PG8_SCHED __builtin_amdgcn_sched_barrier(0)
; template <class Epi>
; __device__ __forceinline__ void gemm_phase(LAS unsigned char* lds, const Gemm g, const StaticOrder& S, const Epi& E) {
;     ...
;             PG8_WAIT_V(6); PG8_BAR; PG8_MMA(1, 1, At, B1); PG8_BAR;
;             PG8_LDB(B0, 1, 0); PG8_SCHED; PG8_LDA(At, 1, 0); PG8_STAGE(PG8_SA(0, 1), a2 + hstep, voffA);
;             PG8_WAIT_L(8); PG8_BAR; PG8_WAIT_L(0); PG8_MMA(0, 0, At, B0); PG8_BAR; PG8_SCHED;
;             PG8_LDB(B1, 1, 1); PG8_STAGE(PG8_SB(1, 0), b3, voffB);
;             PG8_BAR; PG8_WAIT_L(0); PG8_MMA(0, 1, At, B1); PG8_BAR;
;             PG8_LDA(At, 1, 1); PG8_STAGE(PG8_SA(1, 0), a3, voffA);
;             PG8_BAR; PG8_WAIT_L(0); PG8_MMA(1, 0, At, B0); PG8_BAR; PG8_SCHED;
	s_add_u32 s64, s36, 0x40000
	s_addc_u32 s65, s37, 0
	s_add_i32 s66, s52, s44
	v_lshl_add_u64 v[160:161], s[64:65], 0, v[144:145]
	s_mov_b32 m0, s66
	s_nop 0
	global_load_lds_dwordx4 v[160:161], off
	v_lshl_add_u64 v[160:161], s[64:65], 0, v[150:151]
	s_add_i32 m0, s66, 0x2000
	s_nop 0
	global_load_lds_dwordx4 v[160:161], off
	s_waitcnt vmcnt(6)
	s_barrier
	s_setprio 1
	v_mfma_f32_16x16x32_f16 v[52:55], v[212:215], v[180:183], v[52:55]
	v_mfma_f32_16x16x32_f16 v[48:51], v[220:223], v[180:183], v[48:51]
	v_mfma_f32_16x16x32_f16 v[36:39], v[212:215], v[188:191], v[36:39]
	v_mfma_f32_16x16x32_f16 v[32:35], v[220:223], v[188:191], v[32:35]
	v_mfma_f32_16x16x32_f16 v[20:23], v[212:215], v[196:199], v[20:23]
	v_mfma_f32_16x16x32_f16 v[16:19], v[220:223], v[196:199], v[16:19]
	v_mfma_f32_16x16x32_f16 v[4:7], v[212:215], v[204:207], v[4:7]
	v_mfma_f32_16x16x32_f16 v[0:3], v[220:223], v[204:207], v[0:3]
	v_mfma_f32_16x16x32_f16 v[52:55], v[216:219], v[184:187], v[52:55]
	v_mfma_f32_16x16x32_f16 v[48:51], v[224:227], v[184:187], v[48:51]
	v_mfma_f32_16x16x32_f16 v[36:39], v[216:219], v[192:195], v[36:39]
	v_mfma_f32_16x16x32_f16 v[32:35], v[224:227], v[192:195], v[32:35]
	v_mfma_f32_16x16x32_f16 v[20:23], v[216:219], v[200:203], v[20:23]
	v_mfma_f32_16x16x32_f16 v[16:19], v[224:227], v[200:203], v[16:19]
	v_mfma_f32_16x16x32_f16 v[4:7], v[216:219], v[208:211], v[4:7]
	v_mfma_f32_16x16x32_f16 v[0:3], v[224:227], v[208:211], v[0:3]
	s_setprio 0
	s_add_i32 s64, 0, 0x18000
	v_add_u32_e32 v176, s64, v141
	s_barrier
	ds_read_b128 v[160:163], v176
	ds_read_b128 v[164:167], v176 offset:1024
	ds_read_b128 v[172:175], v176 offset:2048
	ds_read_b128 v[176:179], v176 offset:3072
	s_add_u32 s38, s38, 0x40000
	s_addc_u32 s39, s39, 0
	s_mov_b32 m0, s46
	v_lshl_add_u64 v[212:213], s[38:39], 0, v[142:143]
	ds_read_b128 v[180:183], v169 offset:32768
	ds_read_b128 v[184:187], v169 offset:33792
	ds_read_b128 v[188:191], v169 offset:34816
	ds_read_b128 v[192:195], v169 offset:35840
	ds_read_b128 v[196:199], v169 offset:36864
	ds_read_b128 v[200:203], v169 offset:37888
	ds_read_b128 v[204:207], v169 offset:38912
	ds_read_b128 v[208:211], v169 offset:39936
	global_load_lds_dwordx4 v[212:213], off
	v_lshl_add_u64 v[212:213], s[38:39], 0, v[148:149]
	s_mov_b32 m0, s47
	s_nop 0
	global_load_lds_dwordx4 v[212:213], off
	s_waitcnt lgkmcnt(8)
	s_barrier
	s_waitcnt lgkmcnt(0)
	s_setprio 1
	s_waitcnt lgkmcnt(0)
	v_mfma_f32_16x16x32_f16 v[124:127], v[160:163], v[180:183], v[124:127]
	v_mfma_f32_16x16x32_f16 v[120:123], v[172:175], v[180:183], v[120:123]
	v_mfma_f32_16x16x32_f16 v[108:111], v[160:163], v[188:191], v[108:111]
	v_mfma_f32_16x16x32_f16 v[104:107], v[172:175], v[188:191], v[104:107]
	v_mfma_f32_16x16x32_f16 v[92:95], v[160:163], v[196:199], v[92:95]
	v_mfma_f32_16x16x32_f16 v[88:91], v[172:175], v[196:199], v[88:91]
	v_mfma_f32_16x16x32_f16 v[76:79], v[160:163], v[204:207], v[76:79]
	v_mfma_f32_16x16x32_f16 v[72:75], v[172:175], v[204:207], v[72:75]
	v_mfma_f32_16x16x32_f16 v[124:127], v[164:167], v[184:187], v[124:127]
	v_mfma_f32_16x16x32_f16 v[120:123], v[176:179], v[184:187], v[120:123]
	v_mfma_f32_16x16x32_f16 v[108:111], v[164:167], v[192:195], v[108:111]
	v_mfma_f32_16x16x32_f16 v[104:107], v[176:179], v[192:195], v[104:107]
	v_mfma_f32_16x16x32_f16 v[92:95], v[164:167], v[200:203], v[92:95]
	v_mfma_f32_16x16x32_f16 v[88:91], v[176:179], v[200:203], v[88:91]
	v_mfma_f32_16x16x32_f16 v[76:79], v[164:167], v[208:211], v[76:79]
	v_mfma_f32_16x16x32_f16 v[72:75], v[176:179], v[208:211], v[72:75]
	s_setprio 0
	s_barrier
	s_add_i32 s38, 0, 0x1c000
	s_add_i32 s39, s64, s44
	v_add_u32_e32 v224, s38, v141
	v_lshl_add_u64 v[228:229], v[228:229], 0, s[8:9]
	s_mov_b32 m0, s39
	ds_read_b128 v[212:215], v224
	ds_read_b128 v[216:219], v224 offset:1024
	ds_read_b128 v[220:223], v224 offset:2048
	ds_read_b128 v[224:227], v224 offset:3072
	global_load_lds_dwordx4 v[228:229], off
	v_lshl_add_u64 v[228:229], v[230:231], 0, s[8:9]
	s_add_i32 m0, s39, 0x2000
	s_nop 0
	global_load_lds_dwordx4 v[228:229], off
	s_barrier
	s_waitcnt lgkmcnt(0)
	s_setprio 1
	s_waitcnt lgkmcnt(0)
	v_mfma_f32_16x16x32_f16 v[116:119], v[212:215], v[180:183], v[116:119]
	v_mfma_f32_16x16x32_f16 v[112:115], v[220:223], v[180:183], v[112:115]
	v_mfma_f32_16x16x32_f16 v[100:103], v[212:215], v[188:191], v[100:103]
	v_mfma_f32_16x16x32_f16 v[96:99], v[220:223], v[188:191], v[96:99]
	v_mfma_f32_16x16x32_f16 v[84:87], v[212:215], v[196:199], v[84:87]
	v_mfma_f32_16x16x32_f16 v[80:83], v[220:223], v[196:199], v[80:83]
	v_mfma_f32_16x16x32_f16 v[68:71], v[212:215], v[204:207], v[68:71]
	v_mfma_f32_16x16x32_f16 v[64:67], v[220:223], v[204:207], v[64:67]
	v_mfma_f32_16x16x32_f16 v[116:119], v[216:219], v[184:187], v[116:119]
	v_mfma_f32_16x16x32_f16 v[112:115], v[224:227], v[184:187], v[112:115]
	v_mfma_f32_16x16x32_f16 v[100:103], v[216:219], v[192:195], v[100:103]
	v_mfma_f32_16x16x32_f16 v[96:99], v[224:227], v[192:195], v[96:99]
	v_mfma_f32_16x16x32_f16 v[84:87], v[216:219], v[200:203], v[84:87]
	v_mfma_f32_16x16x32_f16 v[80:83], v[224:227], v[200:203], v[80:83]
	v_mfma_f32_16x16x32_f16 v[68:71], v[216:219], v[208:211], v[68:71]
	v_mfma_f32_16x16x32_f16 v[64:67], v[224:227], v[208:211], v[64:67]
	s_setprio 0
	s_mov_b32 m0, s49
	v_lshl_add_u64 v[228:229], v[232:233], 0, s[8:9]
	s_barrier
	ds_read_b128 v[180:183], v169 offset:49152
	ds_read_b128 v[184:187], v169 offset:50176
	ds_read_b128 v[188:191], v169 offset:51200
	ds_read_b128 v[192:195], v169 offset:52224
	ds_read_b128 v[196:199], v169 offset:53248
	ds_read_b128 v[200:203], v169 offset:54272
	ds_read_b128 v[204:207], v169 offset:55296
	ds_read_b128 v[208:211], v169 offset:56320
	global_load_lds_dwordx4 v[228:229], off
	v_lshl_add_u64 v[228:229], v[234:235], 0, s[8:9]
	s_mov_b32 m0, s50
	s_nop 0
	global_load_lds_dwordx4 v[228:229], off
	s_barrier
; #define PG8_MMA(ai, bj, At, Bt) do { __builtin_amdgcn_s_setprio(1); _Pragma("unroll") for (int m = 0; m < 4; ++m) _Pragma("unroll") for (int n = 0; n < 2; ++n) _Pragma("unroll") for (int k = 0; k < 2; ++k) \
;         acc[ai][bj][m][n] = __builtin_amdgcn_mfma_f32_16x16x32_f16(Bt[n][k], At[m][k], acc[ai][bj][m][n], 0, 0, 0); __builtin_amdgcn_s_setprio(0); } while (0)
; template <class Epi>
; __device__ __forceinline__ void gemm_phase(LAS unsigned char* lds, const Gemm g, const StaticOrder& S, const Epi& E) {
;     ...
;             PG8_WAIT_V(6); PG8_BAR; PG8_MMA(1, 1, At, B1); PG8_BAR;
;         }
;     __device__ __forceinline__ void operator()(const f32x4 (&acc)[2][2][4][2], const pg8::Unit& u, int wr, int wc, int fr, int fq) const {
;         const int row0 = u.pm * 256 + wr * 64 + fr, col0 = u.pn * 256 + wc * 32 + 8 * fq;
; #pragma unroll
;         for (int ai = 0; ai < 2; ++ai)
; #pragma unroll
;             for (int m = 0; m < 4; ++m) {
;                 const int row = row0 + ai * 128 + m * 16;
;                 float ss = 0.f, rstd = 1.f;
;                 if (MODE == 2) rstd = rsqrtf(rowss[row] * (1.f / 1024.f) + EPS);
; #pragma unroll
;                 for (int bj = 0; bj < 2; ++bj) {
;                     const int c = col0 + bj * 128;
;                     f32x4 v0 = acc[ai][bj][m][0], v1 = acc[ai][bj][m][1];
;                     if (MODE == 1) {
;                         const float* rp = res + (size_t)row * ldres + c;
;                         v0 += *(const f32x4*)rp; v1 += *(const f32x4*)(rp + 4);
;                     }
;                     if (MODE == 3) {
;                         const h16x8 r8 = *(const h16x8*)(res16 + (size_t)row * ldres + c);
; #pragma unroll
;                         for (int j = 0; j < 4; ++j) { v0[j] += (float)r8[j]; v1[j] += (float)r8[4 + j]; }
;                     }
;                     if (MODE == 1 || MODE == 3) {
;                         ss += v0[0] * v0[0] + v0[1] * v0[1] + v0[2] * v0[2] + v0[3] * v0[3] + v1[0] * v1[0] + v1[1] * v1[1] + v1[2] * v1[2] + v1[3] * v1[3];
;                     }
;                     if (MODE == 2) {
; #pragma unroll
;                         for (int j = 0; j < 4; ++j) { float a = fmaxf(v0[j] * rstd, 0.f), b = fmaxf(v1[j] * rstd, 0.f); v0[j] = a * a; v1[j] = b * b; }
;                     }
;                     *(h16x8*)(o16 + (size_t)row * ld16 + c) = pack8(v0, v1);
	s_waitcnt lgkmcnt(0)
	s_setprio 1
	s_waitcnt lgkmcnt(0)
	v_mfma_f32_16x16x32_f16 v[60:63], v[160:163], v[180:183], v[60:63]
	v_mfma_f32_16x16x32_f16 v[56:59], v[172:175], v[180:183], v[56:59]
	v_mfma_f32_16x16x32_f16 v[44:47], v[160:163], v[188:191], v[44:47]
	v_mfma_f32_16x16x32_f16 v[40:43], v[172:175], v[188:191], v[40:43]
	v_mfma_f32_16x16x32_f16 v[28:31], v[160:163], v[196:199], v[28:31]
	v_mfma_f32_16x16x32_f16 v[24:27], v[172:175], v[196:199], v[24:27]
	v_mfma_f32_16x16x32_f16 v[12:15], v[160:163], v[204:207], v[12:15]
	v_mfma_f32_16x16x32_f16 v[8:11], v[172:175], v[204:207], v[8:11]
	v_mfma_f32_16x16x32_f16 v[60:63], v[164:167], v[184:187], v[60:63]
	v_mfma_f32_16x16x32_f16 v[56:59], v[176:179], v[184:187], v[56:59]
	v_mfma_f32_16x16x32_f16 v[44:47], v[164:167], v[192:195], v[44:47]
	v_mfma_f32_16x16x32_f16 v[40:43], v[176:179], v[192:195], v[40:43]
	v_mfma_f32_16x16x32_f16 v[28:31], v[164:167], v[200:203], v[28:31]
	v_mfma_f32_16x16x32_f16 v[24:27], v[176:179], v[200:203], v[24:27]
	v_mfma_f32_16x16x32_f16 v[12:15], v[164:167], v[208:211], v[12:15]
	v_mfma_f32_16x16x32_f16 v[8:11], v[176:179], v[208:211], v[8:11]
	s_setprio 0
	s_barrier
	s_add_u32 s36, s36, 0x40080
	s_addc_u32 s37, s37, 0
	s_add_i32 s38, s38, s44
	v_lshl_add_u64 v[160:161], s[36:37], 0, v[144:145]
	s_mov_b32 m0, s38
	s_nop 0
	global_load_lds_dwordx4 v[160:161], off
	v_lshl_add_u64 v[160:161], s[36:37], 0, v[150:151]
	s_add_i32 m0, s38, 0x2000
	s_nop 0
	global_load_lds_dwordx4 v[160:161], off
	s_waitcnt vmcnt(6)
	s_barrier
	s_setprio 1
	v_mfma_f32_16x16x32_f16 v[52:55], v[212:215], v[180:183], v[52:55]
	v_mfma_f32_16x16x32_f16 v[48:51], v[220:223], v[180:183], v[48:51]
	v_mfma_f32_16x16x32_f16 v[36:39], v[212:215], v[188:191], v[36:39]
	v_mfma_f32_16x16x32_f16 v[32:35], v[220:223], v[188:191], v[32:35]
	v_mfma_f32_16x16x32_f16 v[20:23], v[212:215], v[196:199], v[20:23]
	v_mfma_f32_16x16x32_f16 v[16:19], v[220:223], v[196:199], v[16:19]
	v_mfma_f32_16x16x32_f16 v[4:7], v[212:215], v[204:207], v[4:7]
	v_mfma_f32_16x16x32_f16 v[0:3], v[220:223], v[204:207], v[0:3]
	v_mfma_f32_16x16x32_f16 v[52:55], v[216:219], v[184:187], v[52:55]
	v_mfma_f32_16x16x32_f16 v[48:51], v[224:227], v[184:187], v[48:51]
	v_mfma_f32_16x16x32_f16 v[36:39], v[216:219], v[192:195], v[36:39]
	v_mfma_f32_16x16x32_f16 v[32:35], v[224:227], v[192:195], v[32:35]
	v_mfma_f32_16x16x32_f16 v[20:23], v[216:219], v[200:203], v[20:23]
	v_mfma_f32_16x16x32_f16 v[16:19], v[224:227], v[200:203], v[16:19]
	v_mfma_f32_16x16x32_f16 v[4:7], v[216:219], v[208:211], v[4:7]
	v_mfma_f32_16x16x32_f16 v[0:3], v[224:227], v[208:211], v[0:3]
	s_setprio 0
	s_add_i32 s63, s63, 2
	s_add_u32 s0, s0, 0x100
	s_addc_u32 s1, s1, 0
	s_add_u32 s61, s61, 0x100
	s_addc_u32 s62, s62, 0
	s_cmp_gt_u32 s63, 13
	s_barrier
	s_cbranch_scc0 .LBB0_483
	v_lshl_add_u32 v166, s34, 8, v139
	v_ashrrev_i32_e32 v167, 31, v166
	v_lshl_add_u64 v[160:161], v[166:167], 2, s[14:15]
	global_load_dword v176, v[160:161], off
	global_load_dword v182, v[160:161], off offset:64
	global_load_dword v183, v[160:161], off offset:128
	global_load_dword v184, v[160:161], off offset:192
	global_load_dword v185, v[160:161], off offset:512
	global_load_dword v186, v[160:161], off offset:576
	global_load_dword v187, v[160:161], off offset:640
	global_load_dword v188, v[160:161], off offset:704
	v_lshl_or_b32 v162, s58, 8, v147
	v_ashrrev_i32_e32 v163, 31, v162
	v_lshlrev_b64 v[164:165], 1, v[162:163]
	v_lshlrev_b64 v[174:175], 13, v[166:167]
	v_or_b32_e32 v172, 16, v166
	v_ashrrev_i32_e32 v173, 31, v172
	s_mov_b32 s58, s24
	s_mov_b32 s34, s26
	s_mov_b64 s[36:37], s[30:31]
	s_mov_b64 s[38:39], s[28:29]
	s_waitcnt vmcnt(0)
	v_fmamk_f32 v162, v176, 0x3a800000, v171
	v_mul_f32_e32 v163, 0x4b800000, v162
	v_cmp_gt_f32_e32 vcc, s53, v162
	s_nop 1
	v_cndmask_b32_e32 v162, v162, v163, vcc
	v_rsq_f32_e32 v167, v162
	v_lshl_add_u64 v[162:163], s[12:13], 0, v[174:175]
	v_lshl_add_u64 v[162:163], v[162:163], 0, v[164:165]
	v_lshl_add_u64 v[174:175], v[172:173], 2, s[14:15]
	v_mul_f32_e32 v176, 0x45800000, v167
	v_cndmask_b32_e32 v167, v167, v176, vcc
	v_mul_f32_e32 v120, v120, v167
	v_mul_f32_e32 v125, v125, v167
	v_mul_f32_e32 v121, v121, v167
	v_mul_f32_e32 v126, v126, v167
	v_mul_f32_e32 v122, v122, v167
	v_mul_f32_e32 v127, v127, v167
	v_mul_f32_e32 v124, v124, v167
	v_mul_f32_e32 v123, v123, v167
	v_mul_f32_e32 v176, v116, v167
	v_mul_f32_e32 v177, v112, v167
	v_mul_f32_e32 v178, v117, v167
	v_mul_f32_e32 v179, v113, v167
	v_mul_f32_e32 v118, v118, v167
	v_mul_f32_e32 v180, v114, v167
	v_mul_f32_e32 v181, v119, v167
	v_mul_f32_e32 v167, v115, v167
	v_max_f32_e32 v113, 0, v120
	v_max_f32_e32 v114, 0, v125
	v_max_f32_e32 v116, 0, v121
	v_max_f32_e32 v115, 0, v126
	v_max_f32_e32 v117, 0, v122
	v_max_f32_e32 v112, 0, v127
	v_max_f32_e32 v124, 0, v124
	v_max_f32_e32 v125, 0, v123
	v_max_f32_e32 v119, 0, v177
	v_max_f32_e32 v120, 0, v178
	v_max_f32_e32 v122, 0, v179
	v_max_f32_e32 v121, 0, v118
	v_max_f32_e32 v123, 0, v180
	v_max_f32_e32 v118, 0, v181
	v_pk_mul_f32 v[114:115], v[114:115], v[114:115]
	v_pk_mul_f32 v[112:113], v[112:113], v[112:113]
	v_pk_mul_f32 v[116:117], v[116:117], v[116:117]
	v_max_f32_e32 v126, 0, v176
	v_fma_mixlo_f16 v124, v124, v124, 0
	v_pk_mul_f32 v[120:121], v[120:121], v[120:121]
	v_pk_mul_f32 v[118:119], v[118:119], v[118:119]
	v_pk_mul_f32 v[122:123], v[122:123], v[122:123]
	v_cvt_pk_f16_f32 v114, v114, v115
	v_cvt_pk_f16_f32 v115, v112, v113
	v_cvt_pk_f16_f32 v116, v116, v117
	v_fma_mixlo_f16 v126, v126, v126, 0
	v_cvt_pk_f16_f32 v117, v120, v121
	v_cvt_pk_f16_f32 v118, v118, v119
	v_cvt_pk_f16_f32 v119, v122, v123
	v_pack_b32_f16 v112, v124, v114
;     __device__ __forceinline__ void operator()(const f32x4 (&acc)[2][2][4][2], const pg8::Unit& u, int wr, int wc, int fr, int fq) const {
;         const int row0 = u.pm * 256 + wr * 64 + fr, col0 = u.pn * 256 + wc * 32 + 8 * fq;
; #pragma unroll
;         for (int ai = 0; ai < 2; ++ai)
; #pragma unroll
;             for (int m = 0; m < 4; ++m) {
;                 const int row = row0 + ai * 128 + m * 16;
;                 float ss = 0.f, rstd = 1.f;
;                 if (MODE == 2) rstd = rsqrtf(rowss[row] * (1.f / 1024.f) + EPS);
; #pragma unroll
;                 for (int bj = 0; bj < 2; ++bj) {
;                     const int c = col0 + bj * 128;
;                     f32x4 v0 = acc[ai][bj][m][0], v1 = acc[ai][bj][m][1];
;                     if (MODE == 1) {
;                         const float* rp = res + (size_t)row * ldres + c;
;                         v0 += *(const f32x4*)rp; v1 += *(const f32x4*)(rp + 4);
;                     }
;                     if (MODE == 3) {
;                         const h16x8 r8 = *(const h16x8*)(res16 + (size_t)row * ldres + c);
; #pragma unroll
;                         for (int j = 0; j < 4; ++j) { v0[j] += (float)r8[j]; v1[j] += (float)r8[4 + j]; }
;                     }
;                     if (MODE == 1 || MODE == 3) {
;                         ss += v0[0] * v0[0] + v0[1] * v0[1] + v0[2] * v0[2] + v0[3] * v0[3] + v1[0] * v1[0] + v1[1] * v1[1] + v1[2] * v1[2] + v1[3] * v1[3];
;                     }
;                     if (MODE == 2) {
; #pragma unroll
;                         for (int j = 0; j < 4; ++j) { float a = fmaxf(v0[j] * rstd, 0.f), b = fmaxf(v1[j] * rstd, 0.f); v0[j] = a * a; v1[j] = b * b; }
;                     }
;                     *(h16x8*)(o16 + (size_t)row * ld16 + c) = pack8(v0, v1);
	v_alignbit_b32 v113, v115, v114, 16
	v_alignbit_b32 v114, v116, v115, 16
	v_lshrrev_b32_e32 v115, 16, v116
	v_max_f32_e32 v127, 0, v167
	v_pack_b32_f16 v116, v126, v117
	v_alignbit_b32 v117, v118, v117, 16
	v_alignbit_b32 v118, v119, v118, 16
	v_lshrrev_b32_e32 v119, 16, v119
	v_fma_mixhi_f16 v115, v125, v125, 0
	v_fma_mixhi_f16 v119, v127, v127, 0
	global_store_dwordx4 v[162:163], v[112:115], off
	global_store_dwordx4 v[162:163], v[116:119], off offset:256
	s_nop 1
	v_mov_b32_e32 v116, v182
	v_lshlrev_b64 v[114:115], 13, v[172:173]
	v_or_b32_e32 v112, 32, v166
	v_lshl_add_u64 v[114:115], s[12:13], 0, v[114:115]
	v_ashrrev_i32_e32 v113, 31, v112
	v_lshl_add_u64 v[114:115], v[114:115], 0, v[164:165]
	s_nop 0
	v_fmamk_f32 v116, v116, 0x3a800000, v171
	v_mul_f32_e32 v117, 0x4b800000, v116
	v_cmp_gt_f32_e32 vcc, s53, v116
	s_nop 1
	v_cndmask_b32_e32 v116, v116, v117, vcc
	v_rsq_f32_e32 v118, v116
	v_lshl_add_u64 v[116:117], v[112:113], 2, s[14:15]
	v_mul_f32_e32 v119, 0x45800000, v118
	v_cndmask_b32_e32 v118, v118, v119, vcc
	v_mul_f32_e32 v104, v104, v118
	v_mul_f32_e32 v109, v109, v118
	v_mul_f32_e32 v105, v105, v118
	v_mul_f32_e32 v110, v110, v118
	v_mul_f32_e32 v106, v106, v118
	v_mul_f32_e32 v111, v111, v118
	v_mul_f32_e32 v108, v108, v118
	v_mul_f32_e32 v107, v107, v118
	v_mul_f32_e32 v119, v100, v118
	v_mul_f32_e32 v120, v96, v118
	v_mul_f32_e32 v121, v101, v118
	v_mul_f32_e32 v122, v97, v118
	v_mul_f32_e32 v102, v102, v118
	v_mul_f32_e32 v123, v98, v118
	v_mul_f32_e32 v124, v103, v118
	v_mul_f32_e32 v118, v99, v118
	v_max_f32_e32 v97, 0, v104
	v_max_f32_e32 v98, 0, v109
	v_max_f32_e32 v100, 0, v105
	v_max_f32_e32 v99, 0, v110
	v_max_f32_e32 v101, 0, v106
	v_max_f32_e32 v96, 0, v111
	v_max_f32_e32 v108, 0, v108
	v_max_f32_e32 v109, 0, v107
	v_max_f32_e32 v103, 0, v120
	v_max_f32_e32 v104, 0, v121
	v_max_f32_e32 v106, 0, v122
	v_max_f32_e32 v105, 0, v102
	v_max_f32_e32 v107, 0, v123
	v_max_f32_e32 v102, 0, v124
	v_pk_mul_f32 v[98:99], v[98:99], v[98:99]
	v_pk_mul_f32 v[96:97], v[96:97], v[96:97]
	v_pk_mul_f32 v[100:101], v[100:101], v[100:101]
	v_max_f32_e32 v110, 0, v119
	v_fma_mixlo_f16 v108, v108, v108, 0
	v_pk_mul_f32 v[104:105], v[104:105], v[104:105]
	v_pk_mul_f32 v[102:103], v[102:103], v[102:103]
	v_pk_mul_f32 v[106:107], v[106:107], v[106:107]
	v_cvt_pk_f16_f32 v98, v98, v99
	v_cvt_pk_f16_f32 v99, v96, v97
	v_cvt_pk_f16_f32 v100, v100, v101
	v_fma_mixlo_f16 v110, v110, v110, 0
	v_cvt_pk_f16_f32 v101, v104, v105
	v_cvt_pk_f16_f32 v102, v102, v103
	v_cvt_pk_f16_f32 v103, v106, v107
	v_pack_b32_f16 v96, v108, v98
	v_alignbit_b32 v97, v99, v98, 16
	v_alignbit_b32 v98, v100, v99, 16
	v_lshrrev_b32_e32 v99, 16, v100
	v_max_f32_e32 v111, 0, v118
	v_pack_b32_f16 v100, v110, v101
	v_alignbit_b32 v101, v102, v101, 16
	v_alignbit_b32 v102, v103, v102, 16
	v_lshrrev_b32_e32 v103, 16, v103
	v_fma_mixhi_f16 v99, v109, v109, 0
	v_fma_mixhi_f16 v103, v111, v111, 0
	global_store_dwordx4 v[114:115], v[96:99], off
	global_store_dwordx4 v[114:115], v[100:103], off offset:256
	s_nop 1
	v_mov_b32_e32 v100, v183
	v_lshlrev_b64 v[98:99], 13, v[112:113]
	v_or_b32_e32 v96, 48, v166
	v_lshl_add_u64 v[98:99], s[12:13], 0, v[98:99]
	v_ashrrev_i32_e32 v97, 31, v96
	v_lshl_add_u64 v[98:99], v[98:99], 0, v[164:165]
	s_nop 0
	v_fmamk_f32 v100, v100, 0x3a800000, v171
	v_mul_f32_e32 v101, 0x4b800000, v100
	v_cmp_gt_f32_e32 vcc, s53, v100
	s_nop 1
	v_cndmask_b32_e32 v100, v100, v101, vcc
	v_rsq_f32_e32 v102, v100
	v_lshl_add_u64 v[100:101], v[96:97], 2, s[14:15]
	v_mul_f32_e32 v103, 0x45800000, v102
	v_cndmask_b32_e32 v102, v102, v103, vcc
	v_mul_f32_e32 v88, v88, v102
	v_mul_f32_e32 v93, v93, v102
	v_mul_f32_e32 v89, v89, v102
	v_mul_f32_e32 v94, v94, v102
	v_mul_f32_e32 v90, v90, v102
	v_mul_f32_e32 v95, v95, v102
	v_mul_f32_e32 v92, v92, v102
	v_mul_f32_e32 v91, v91, v102
	v_mul_f32_e32 v103, v84, v102
	v_mul_f32_e32 v104, v80, v102
	v_mul_f32_e32 v105, v85, v102
	v_mul_f32_e32 v106, v81, v102
	v_mul_f32_e32 v86, v86, v102
	v_mul_f32_e32 v107, v82, v102
	v_mul_f32_e32 v108, v87, v102
	v_mul_f32_e32 v102, v83, v102
	v_max_f32_e32 v81, 0, v88
	v_max_f32_e32 v82, 0, v93
	v_max_f32_e32 v84, 0, v89
	v_max_f32_e32 v83, 0, v94
	v_max_f32_e32 v85, 0, v90
	v_max_f32_e32 v80, 0, v95
	v_max_f32_e32 v92, 0, v92
	v_max_f32_e32 v93, 0, v91
	v_max_f32_e32 v87, 0, v104
	v_max_f32_e32 v88, 0, v105
	v_max_f32_e32 v90, 0, v106
	v_max_f32_e32 v89, 0, v86
	v_max_f32_e32 v91, 0, v107
	v_max_f32_e32 v86, 0, v108
	v_pk_mul_f32 v[82:83], v[82:83], v[82:83]
	v_pk_mul_f32 v[80:81], v[80:81], v[80:81]
	v_pk_mul_f32 v[84:85], v[84:85], v[84:85]
	v_max_f32_e32 v94, 0, v103
	v_fma_mixlo_f16 v92, v92, v92, 0
	v_pk_mul_f32 v[88:89], v[88:89], v[88:89]
	v_pk_mul_f32 v[86:87], v[86:87], v[86:87]
	v_pk_mul_f32 v[90:91], v[90:91], v[90:91]
	v_cvt_pk_f16_f32 v82, v82, v83
	v_cvt_pk_f16_f32 v83, v80, v81
	v_cvt_pk_f16_f32 v84, v84, v85
	v_fma_mixlo_f16 v94, v94, v94, 0
	v_cvt_pk_f16_f32 v85, v88, v89
	v_cvt_pk_f16_f32 v86, v86, v87
	v_cvt_pk_f16_f32 v87, v90, v91
	v_pack_b32_f16 v80, v92, v82
	v_alignbit_b32 v81, v83, v82, 16
	v_alignbit_b32 v82, v84, v83, 16
	v_lshrrev_b32_e32 v83, 16, v84
	v_max_f32_e32 v95, 0, v102
	v_pack_b32_f16 v84, v94, v85
	v_alignbit_b32 v85, v86, v85, 16
	v_alignbit_b32 v86, v87, v86, 16
	v_lshrrev_b32_e32 v87, 16, v87
	v_fma_mixhi_f16 v83, v93, v93, 0
	v_fma_mixhi_f16 v87, v95, v95, 0
	global_store_dwordx4 v[98:99], v[80:83], off
	global_store_dwordx4 v[98:99], v[84:87], off offset:256
	s_nop 1
	v_mov_b32_e32 v80, v184
	s_nop 0
	v_fmamk_f32 v80, v80, 0x3a800000, v171
	v_mul_f32_e32 v81, 0x4b800000, v80
	v_cmp_gt_f32_e32 vcc, s53, v80
	s_nop 1
	v_cndmask_b32_e32 v80, v80, v81, vcc
;     __device__ __forceinline__ void operator()(const f32x4 (&acc)[2][2][4][2], const pg8::Unit& u, int wr, int wc, int fr, int fq) const {
;         const int row0 = u.pm * 256 + wr * 64 + fr, col0 = u.pn * 256 + wc * 32 + 8 * fq;
; #pragma unroll
;         for (int ai = 0; ai < 2; ++ai)
; #pragma unroll
;             for (int m = 0; m < 4; ++m) {
;                 const int row = row0 + ai * 128 + m * 16;
;                 float ss = 0.f, rstd = 1.f;
;                 if (MODE == 2) rstd = rsqrtf(rowss[row] * (1.f / 1024.f) + EPS);
; #pragma unroll
;                 for (int bj = 0; bj < 2; ++bj) {
;                     const int c = col0 + bj * 128;
;                     f32x4 v0 = acc[ai][bj][m][0], v1 = acc[ai][bj][m][1];
;                     if (MODE == 1) {
;                         const float* rp = res + (size_t)row * ldres + c;
;                         v0 += *(const f32x4*)rp; v1 += *(const f32x4*)(rp + 4);
;                     }
;                     if (MODE == 3) {
;                         const h16x8 r8 = *(const h16x8*)(res16 + (size_t)row * ldres + c);
; #pragma unroll
;                         for (int j = 0; j < 4; ++j) { v0[j] += (float)r8[j]; v1[j] += (float)r8[4 + j]; }
;                     }
;                     if (MODE == 1 || MODE == 3) {
;                         ss += v0[0] * v0[0] + v0[1] * v0[1] + v0[2] * v0[2] + v0[3] * v0[3] + v1[0] * v1[0] + v1[1] * v1[1] + v1[2] * v1[2] + v1[3] * v1[3];
;                     }
;                     if (MODE == 2) {
; #pragma unroll
;                         for (int j = 0; j < 4; ++j) { float a = fmaxf(v0[j] * rstd, 0.f), b = fmaxf(v1[j] * rstd, 0.f); v0[j] = a * a; v1[j] = b * b; }
;                     }
;                     *(h16x8*)(o16 + (size_t)row * ld16 + c) = pack8(v0, v1);
	v_rsq_f32_e32 v82, v80
	v_lshlrev_b64 v[80:81], 13, v[96:97]
	v_lshl_add_u64 v[80:81], s[12:13], 0, v[80:81]
	v_lshl_add_u64 v[80:81], v[80:81], 0, v[164:165]
	v_mul_f32_e32 v83, 0x45800000, v82
	v_cndmask_b32_e32 v82, v82, v83, vcc
	v_mul_f32_e32 v72, v72, v82
	v_mul_f32_e32 v77, v77, v82
	v_mul_f32_e32 v73, v73, v82
	v_mul_f32_e32 v78, v78, v82
	v_mul_f32_e32 v74, v74, v82
	v_mul_f32_e32 v79, v79, v82
	v_mul_f32_e32 v76, v76, v82
	v_mul_f32_e32 v75, v75, v82
	v_mul_f32_e32 v83, v68, v82
	v_mul_f32_e32 v84, v64, v82
	v_mul_f32_e32 v85, v69, v82
	v_mul_f32_e32 v86, v65, v82
	v_mul_f32_e32 v70, v70, v82
	v_mul_f32_e32 v87, v66, v82
	v_mul_f32_e32 v88, v71, v82
	v_mul_f32_e32 v82, v67, v82
	v_max_f32_e32 v65, 0, v72
	v_max_f32_e32 v66, 0, v77
	v_max_f32_e32 v68, 0, v73
	v_max_f32_e32 v67, 0, v78
	v_max_f32_e32 v69, 0, v74
	v_max_f32_e32 v64, 0, v79
	v_max_f32_e32 v76, 0, v76
	v_max_f32_e32 v77, 0, v75
	v_max_f32_e32 v71, 0, v84
	v_max_f32_e32 v72, 0, v85
	v_max_f32_e32 v74, 0, v86
	v_max_f32_e32 v73, 0, v70
	v_max_f32_e32 v75, 0, v87
	v_max_f32_e32 v70, 0, v88
	v_pk_mul_f32 v[66:67], v[66:67], v[66:67]
	v_pk_mul_f32 v[64:65], v[64:65], v[64:65]
	v_pk_mul_f32 v[68:69], v[68:69], v[68:69]
	v_max_f32_e32 v78, 0, v83
	v_fma_mixlo_f16 v76, v76, v76, 0
	v_pk_mul_f32 v[72:73], v[72:73], v[72:73]
	v_pk_mul_f32 v[70:71], v[70:71], v[70:71]
	v_pk_mul_f32 v[74:75], v[74:75], v[74:75]
	v_cvt_pk_f16_f32 v66, v66, v67
	v_cvt_pk_f16_f32 v67, v64, v65
	v_cvt_pk_f16_f32 v68, v68, v69
	v_fma_mixlo_f16 v78, v78, v78, 0
	v_cvt_pk_f16_f32 v69, v72, v73
	v_cvt_pk_f16_f32 v70, v70, v71
	v_cvt_pk_f16_f32 v71, v74, v75
	v_pack_b32_f16 v64, v76, v66
	v_alignbit_b32 v65, v67, v66, 16
	v_alignbit_b32 v66, v68, v67, 16
	v_lshrrev_b32_e32 v67, 16, v68
	v_max_f32_e32 v79, 0, v82
	v_pack_b32_f16 v68, v78, v69
	v_alignbit_b32 v69, v70, v69, 16
	v_alignbit_b32 v70, v71, v70, 16
	v_lshrrev_b32_e32 v71, 16, v71
	v_fma_mixhi_f16 v67, v77, v77, 0
	v_fma_mixhi_f16 v71, v79, v79, 0
	global_store_dwordx4 v[80:81], v[64:67], off
	global_store_dwordx4 v[80:81], v[68:71], off offset:256
	s_nop 1
	v_mov_b32_e32 v66, v185
	v_lshl_add_u64 v[64:65], v[162:163], 0, s[16:17]
	s_nop 0
	v_fmamk_f32 v66, v66, 0x3a800000, v171
	v_mul_f32_e32 v67, 0x4b800000, v66
	v_cmp_gt_f32_e32 vcc, s53, v66
	s_nop 1
	v_cndmask_b32_e32 v66, v66, v67, vcc
	v_rsq_f32_e32 v68, v66
	v_add_co_u32_e64 v66, s[0:1], s54, v162
	v_mul_f32_e32 v69, 0x45800000, v68
	v_cndmask_b32_e32 v68, v68, v69, vcc
	v_mul_f32_e32 v56, v56, v68
	v_mul_f32_e32 v61, v61, v68
	v_mul_f32_e32 v57, v57, v68
	v_mul_f32_e32 v62, v62, v68
	v_mul_f32_e32 v58, v58, v68
	v_mul_f32_e32 v63, v63, v68
	v_mul_f32_e32 v60, v60, v68
	v_mul_f32_e32 v59, v59, v68
	v_mul_f32_e32 v69, v52, v68
	v_mul_f32_e32 v70, v48, v68
	v_mul_f32_e32 v71, v53, v68
	v_mul_f32_e32 v72, v49, v68
	v_mul_f32_e32 v54, v54, v68
	v_mul_f32_e32 v73, v50, v68
	v_mul_f32_e32 v74, v55, v68
	v_mul_f32_e32 v68, v51, v68
	v_max_f32_e32 v49, 0, v56
	v_max_f32_e32 v50, 0, v61
	v_max_f32_e32 v52, 0, v57
	v_max_f32_e32 v51, 0, v62
	v_max_f32_e32 v53, 0, v58
	v_max_f32_e32 v48, 0, v63
	v_max_f32_e32 v60, 0, v60
	v_max_f32_e32 v61, 0, v59
	v_max_f32_e32 v55, 0, v70
	v_max_f32_e32 v56, 0, v71
	v_max_f32_e32 v58, 0, v72
	v_max_f32_e32 v57, 0, v54
	v_max_f32_e32 v59, 0, v73
	v_max_f32_e32 v54, 0, v74
	v_pk_mul_f32 v[50:51], v[50:51], v[50:51]
	v_pk_mul_f32 v[48:49], v[48:49], v[48:49]
	v_pk_mul_f32 v[52:53], v[52:53], v[52:53]
	v_max_f32_e32 v62, 0, v69
	v_fma_mixlo_f16 v60, v60, v60, 0
	v_pk_mul_f32 v[56:57], v[56:57], v[56:57]
	v_pk_mul_f32 v[54:55], v[54:55], v[54:55]
	v_pk_mul_f32 v[58:59], v[58:59], v[58:59]
	v_cvt_pk_f16_f32 v50, v50, v51
	v_cvt_pk_f16_f32 v51, v48, v49
	v_cvt_pk_f16_f32 v52, v52, v53
	v_fma_mixlo_f16 v62, v62, v62, 0
	v_cvt_pk_f16_f32 v53, v56, v57
	v_cvt_pk_f16_f32 v54, v54, v55
	v_cvt_pk_f16_f32 v55, v58, v59
	v_pack_b32_f16 v48, v60, v50
	v_alignbit_b32 v49, v51, v50, 16
	v_alignbit_b32 v50, v52, v51, 16
	v_lshrrev_b32_e32 v51, 16, v52
	v_addc_co_u32_e64 v67, s[0:1], 0, v163, s[0:1]
	v_max_f32_e32 v63, 0, v68
	v_pack_b32_f16 v52, v62, v53
	v_alignbit_b32 v53, v54, v53, 16
	v_alignbit_b32 v54, v55, v54, 16
	v_lshrrev_b32_e32 v55, 16, v55
	v_fma_mixhi_f16 v51, v61, v61, 0
	v_fma_mixhi_f16 v55, v63, v63, 0
	global_store_dwordx4 v[66:67], v[48:51], off
	global_store_dwordx4 v[64:65], v[52:55], off offset:256
	s_nop 1
	v_mov_b32_e32 v50, v186
	v_lshl_add_u64 v[48:49], v[162:163], 0, s[18:19]
	s_nop 0
	v_fmamk_f32 v50, v50, 0x3a800000, v171
	v_mul_f32_e32 v51, 0x4b800000, v50
	v_cmp_gt_f32_e32 vcc, s53, v50
	s_nop 1
	v_cndmask_b32_e32 v50, v50, v51, vcc
	v_rsq_f32_e32 v52, v50
	v_add_co_u32_e64 v50, s[0:1], s55, v162
	v_mul_f32_e32 v53, 0x45800000, v52
	v_cndmask_b32_e32 v52, v52, v53, vcc
	v_mul_f32_e32 v40, v40, v52
	v_mul_f32_e32 v45, v45, v52
	v_mul_f32_e32 v41, v41, v52
	v_mul_f32_e32 v46, v46, v52
	v_mul_f32_e32 v42, v42, v52
	v_mul_f32_e32 v47, v47, v52
	v_mul_f32_e32 v44, v44, v52
	v_mul_f32_e32 v43, v43, v52
	v_mul_f32_e32 v53, v36, v52
	v_mul_f32_e32 v54, v32, v52
	v_mul_f32_e32 v55, v37, v52
	v_mul_f32_e32 v56, v33, v52
	v_mul_f32_e32 v38, v38, v52
	v_mul_f32_e32 v57, v34, v52
	v_mul_f32_e32 v58, v39, v52
	v_mul_f32_e32 v52, v35, v52
	v_max_f32_e32 v33, 0, v40
	v_max_f32_e32 v34, 0, v45
	v_max_f32_e32 v36, 0, v41
	v_max_f32_e32 v35, 0, v46
	v_max_f32_e32 v37, 0, v42
	v_max_f32_e32 v32, 0, v47
	v_max_f32_e32 v44, 0, v44
	v_max_f32_e32 v45, 0, v43
	v_max_f32_e32 v39, 0, v54
	v_max_f32_e32 v40, 0, v55
	v_max_f32_e32 v42, 0, v56
	v_max_f32_e32 v41, 0, v38
	v_max_f32_e32 v43, 0, v57
	v_max_f32_e32 v38, 0, v58
	v_pk_mul_f32 v[34:35], v[34:35], v[34:35]
;     __device__ __forceinline__ void operator()(const f32x4 (&acc)[2][2][4][2], const pg8::Unit& u, int wr, int wc, int fr, int fq) const {
;         const int row0 = u.pm * 256 + wr * 64 + fr, col0 = u.pn * 256 + wc * 32 + 8 * fq;
; #pragma unroll
;         for (int ai = 0; ai < 2; ++ai)
; #pragma unroll
;             for (int m = 0; m < 4; ++m) {
;                 const int row = row0 + ai * 128 + m * 16;
;                 float ss = 0.f, rstd = 1.f;
;                 if (MODE == 2) rstd = rsqrtf(rowss[row] * (1.f / 1024.f) + EPS);
; #pragma unroll
;                 for (int bj = 0; bj < 2; ++bj) {
;                     const int c = col0 + bj * 128;
;                     f32x4 v0 = acc[ai][bj][m][0], v1 = acc[ai][bj][m][1];
;                     if (MODE == 1) {
;                         const float* rp = res + (size_t)row * ldres + c;
;                         v0 += *(const f32x4*)rp; v1 += *(const f32x4*)(rp + 4);
;                     }
;                     if (MODE == 3) {
;                         const h16x8 r8 = *(const h16x8*)(res16 + (size_t)row * ldres + c);
; #pragma unroll
;                         for (int j = 0; j < 4; ++j) { v0[j] += (float)r8[j]; v1[j] += (float)r8[4 + j]; }
;                     }
;                     if (MODE == 1 || MODE == 3) {
;                         ss += v0[0] * v0[0] + v0[1] * v0[1] + v0[2] * v0[2] + v0[3] * v0[3] + v1[0] * v1[0] + v1[1] * v1[1] + v1[2] * v1[2] + v1[3] * v1[3];
;                     }
;                     if (MODE == 2) {
; #pragma unroll
;                         for (int j = 0; j < 4; ++j) { float a = fmaxf(v0[j] * rstd, 0.f), b = fmaxf(v1[j] * rstd, 0.f); v0[j] = a * a; v1[j] = b * b; }
;                     }
;                     *(h16x8*)(o16 + (size_t)row * ld16 + c) = pack8(v0, v1);
	v_pk_mul_f32 v[32:33], v[32:33], v[32:33]
	v_pk_mul_f32 v[36:37], v[36:37], v[36:37]
	v_max_f32_e32 v46, 0, v53
	v_fma_mixlo_f16 v44, v44, v44, 0
	v_pk_mul_f32 v[40:41], v[40:41], v[40:41]
	v_pk_mul_f32 v[38:39], v[38:39], v[38:39]
	v_pk_mul_f32 v[42:43], v[42:43], v[42:43]
	v_cvt_pk_f16_f32 v34, v34, v35
	v_cvt_pk_f16_f32 v35, v32, v33
	v_cvt_pk_f16_f32 v36, v36, v37
	v_fma_mixlo_f16 v46, v46, v46, 0
	v_cvt_pk_f16_f32 v37, v40, v41
	v_cvt_pk_f16_f32 v38, v38, v39
	v_cvt_pk_f16_f32 v39, v42, v43
	v_pack_b32_f16 v32, v44, v34
	v_alignbit_b32 v33, v35, v34, 16
	v_alignbit_b32 v34, v36, v35, 16
	v_lshrrev_b32_e32 v35, 16, v36
	v_addc_co_u32_e64 v51, s[0:1], 0, v163, s[0:1]
	v_max_f32_e32 v47, 0, v52
	v_pack_b32_f16 v36, v46, v37
	v_alignbit_b32 v37, v38, v37, 16
	v_alignbit_b32 v38, v39, v38, 16
	v_lshrrev_b32_e32 v39, 16, v39
	v_fma_mixhi_f16 v35, v45, v45, 0
	v_fma_mixhi_f16 v39, v47, v47, 0
	global_store_dwordx4 v[50:51], v[32:35], off
	global_store_dwordx4 v[48:49], v[36:39], off offset:256
	s_nop 1
	v_mov_b32_e32 v34, v187
	v_lshl_add_u64 v[32:33], v[162:163], 0, s[20:21]
	s_nop 0
	v_fmamk_f32 v34, v34, 0x3a800000, v171
	v_mul_f32_e32 v35, 0x4b800000, v34
	v_cmp_gt_f32_e32 vcc, s53, v34
	s_nop 1
	v_cndmask_b32_e32 v34, v34, v35, vcc
	v_rsq_f32_e32 v36, v34
	v_add_co_u32_e64 v34, s[0:1], s56, v162
	v_mul_f32_e32 v37, 0x45800000, v36
	v_cndmask_b32_e32 v36, v36, v37, vcc
	v_mul_f32_e32 v24, v24, v36
	v_mul_f32_e32 v29, v29, v36
	v_mul_f32_e32 v25, v25, v36
	v_mul_f32_e32 v30, v30, v36
	v_mul_f32_e32 v26, v26, v36
	v_mul_f32_e32 v31, v31, v36
	v_mul_f32_e32 v28, v28, v36
	v_mul_f32_e32 v27, v27, v36
	v_mul_f32_e32 v37, v20, v36
	v_mul_f32_e32 v38, v16, v36
	v_mul_f32_e32 v39, v21, v36
	v_mul_f32_e32 v40, v17, v36
	v_mul_f32_e32 v22, v22, v36
	v_mul_f32_e32 v41, v18, v36
	v_mul_f32_e32 v42, v23, v36
	v_mul_f32_e32 v36, v19, v36
	v_max_f32_e32 v17, 0, v24
	v_max_f32_e32 v18, 0, v29
	v_max_f32_e32 v20, 0, v25
	v_max_f32_e32 v19, 0, v30
	v_max_f32_e32 v21, 0, v26
	v_max_f32_e32 v16, 0, v31
	v_max_f32_e32 v28, 0, v28
	v_max_f32_e32 v29, 0, v27
	v_max_f32_e32 v23, 0, v38
	v_max_f32_e32 v24, 0, v39
	v_max_f32_e32 v26, 0, v40
	v_max_f32_e32 v25, 0, v22
	v_max_f32_e32 v27, 0, v41
	v_max_f32_e32 v22, 0, v42
	v_pk_mul_f32 v[18:19], v[18:19], v[18:19]
	v_pk_mul_f32 v[16:17], v[16:17], v[16:17]
	v_pk_mul_f32 v[20:21], v[20:21], v[20:21]
	v_max_f32_e32 v30, 0, v37
	v_fma_mixlo_f16 v28, v28, v28, 0
	v_pk_mul_f32 v[24:25], v[24:25], v[24:25]
	v_pk_mul_f32 v[22:23], v[22:23], v[22:23]
	v_pk_mul_f32 v[26:27], v[26:27], v[26:27]
	v_cvt_pk_f16_f32 v18, v18, v19
	v_cvt_pk_f16_f32 v19, v16, v17
	v_cvt_pk_f16_f32 v20, v20, v21
	v_fma_mixlo_f16 v30, v30, v30, 0
	v_cvt_pk_f16_f32 v21, v24, v25
	v_cvt_pk_f16_f32 v22, v22, v23
	v_cvt_pk_f16_f32 v23, v26, v27
	v_pack_b32_f16 v16, v28, v18
	v_alignbit_b32 v17, v19, v18, 16
	v_alignbit_b32 v18, v20, v19, 16
	v_lshrrev_b32_e32 v19, 16, v20
	v_addc_co_u32_e64 v35, s[0:1], 0, v163, s[0:1]
	v_max_f32_e32 v31, 0, v36
	v_pack_b32_f16 v20, v30, v21
	v_alignbit_b32 v21, v22, v21, 16
	v_alignbit_b32 v22, v23, v22, 16
	v_lshrrev_b32_e32 v23, 16, v23
	v_fma_mixhi_f16 v19, v29, v29, 0
	v_fma_mixhi_f16 v23, v31, v31, 0
	global_store_dwordx4 v[34:35], v[16:19], off
	global_store_dwordx4 v[32:33], v[20:23], off offset:256
	s_nop 1
	v_mov_b32_e32 v18, v188
	s_and_b64 vcc, exec, s[6:7]
	v_lshl_add_u64 v[16:17], v[162:163], 0, s[22:23]
	s_nop 0
	v_fmamk_f32 v18, v18, 0x3a800000, v171
	v_mul_f32_e32 v19, 0x4b800000, v18
	v_cmp_gt_f32_e64 s[0:1], s53, v18
	s_nop 1
	v_cndmask_b32_e64 v18, v18, v19, s[0:1]
	v_rsq_f32_e32 v20, v18
	v_add_co_u32_e64 v18, s[6:7], s57, v162
	v_mul_f32_e32 v21, 0x45800000, v20
	v_cndmask_b32_e64 v20, v20, v21, s[0:1]
	v_mul_f32_e32 v8, v8, v20
	v_mul_f32_e32 v13, v13, v20
	v_mul_f32_e32 v9, v9, v20
	v_mul_f32_e32 v14, v14, v20
	v_mul_f32_e32 v10, v10, v20
	v_mul_f32_e32 v15, v15, v20
	v_mul_f32_e32 v12, v12, v20
	v_mul_f32_e32 v11, v11, v20
	v_mul_f32_e32 v21, v4, v20
	v_mul_f32_e32 v22, v0, v20
	v_mul_f32_e32 v23, v5, v20
	v_mul_f32_e32 v24, v1, v20
	v_mul_f32_e32 v6, v6, v20
	v_mul_f32_e32 v25, v2, v20
	v_mul_f32_e32 v26, v7, v20
	v_mul_f32_e32 v20, v3, v20
	v_max_f32_e32 v1, 0, v8
	v_max_f32_e32 v2, 0, v13
	v_max_f32_e32 v4, 0, v9
	v_max_f32_e32 v3, 0, v14
	v_max_f32_e32 v5, 0, v10
	v_max_f32_e32 v0, 0, v15
	v_max_f32_e32 v12, 0, v12
	v_max_f32_e32 v13, 0, v11
	v_max_f32_e32 v7, 0, v22
	v_max_f32_e32 v8, 0, v23
	v_max_f32_e32 v10, 0, v24
	v_max_f32_e32 v9, 0, v6
	v_max_f32_e32 v11, 0, v25
	v_max_f32_e32 v6, 0, v26
	v_pk_mul_f32 v[2:3], v[2:3], v[2:3]
	v_pk_mul_f32 v[0:1], v[0:1], v[0:1]
	v_pk_mul_f32 v[4:5], v[4:5], v[4:5]
	v_max_f32_e32 v14, 0, v21
	v_fma_mixlo_f16 v12, v12, v12, 0
	v_pk_mul_f32 v[8:9], v[8:9], v[8:9]
	v_pk_mul_f32 v[6:7], v[6:7], v[6:7]
	v_pk_mul_f32 v[10:11], v[10:11], v[10:11]
	v_cvt_pk_f16_f32 v2, v2, v3
	v_cvt_pk_f16_f32 v3, v0, v1
	v_cvt_pk_f16_f32 v4, v4, v5
	v_fma_mixlo_f16 v14, v14, v14, 0
	v_cvt_pk_f16_f32 v5, v8, v9
	v_cvt_pk_f16_f32 v6, v6, v7
	v_cvt_pk_f16_f32 v7, v10, v11
	v_pack_b32_f16 v0, v12, v2
	v_alignbit_b32 v1, v3, v2, 16
	v_alignbit_b32 v2, v4, v3, 16
	v_lshrrev_b32_e32 v3, 16, v4
	v_addc_co_u32_e64 v19, s[6:7], 0, v163, s[6:7]
	v_max_f32_e32 v15, 0, v20
	v_pack_b32_f16 v4, v14, v5
	v_alignbit_b32 v5, v6, v5, 16
	v_alignbit_b32 v6, v7, v6, 16
	v_lshrrev_b32_e32 v7, 16, v7
	v_fma_mixhi_f16 v3, v13, v13, 0
	v_fma_mixhi_f16 v7, v15, v15, 0
	global_store_dwordx4 v[18:19], v[0:3], off
	global_store_dwordx4 v[16:17], v[4:7], off offset:256
	s_cbranch_vccz .LBB0_476
	s_waitcnt vmcnt(0)
	s_cmpk_gt_u32 s41, 0xff
	s_cbranch_scc1 .LBB0_487
	s_barrier
